# speedup vs baseline: 1.0298x; 1.0025x over previous
;   #define LDA(dst,b,h) for(int m=0;m<4;++m)for(int k=0;k<2;++k) \
;     dst[m][k]=*reinterpret_cast<const bf16x8*>((char*)SA(b,h)+lds_byte(wr*64+m*16+fr,k*32+fq*8))
;   #define LDB(dst,b,h) for(int n=0;n<2;++n)for(int k=0;k<2;++k) \
;     dst[n][k]=*reinterpret_cast<const bf16x8*>((char*)SB(b,h)+lds_byte(wc*32+n*16+fr,k*32+fq*8))
;   #define MMA(ai,bj,At,Bt_) do{__builtin_amdgcn_s_setprio(1); \
;     for(int m=0;m<4;++m)for(int n=0;n<2;++n)for(int k=0;k<2;++k) \
;       acc[ai][bj][m][n]=__builtin_amdgcn_mfma_f32_16x16x32_bf16(Bt_[n][k],At[m][k],acc[ai][bj][m][n],0,0,0); \
;     __builtin_amdgcn_s_setprio(0);}while(0)
;   #define WAIT_V(n) asm volatile("s_waitcnt vmcnt(" #n ")":::"memory")
;   #define WAIT_L(n) asm volatile("s_waitcnt lgkmcnt(" #n ")":::"memory")
;   #define BAR __builtin_amdgcn_s_barrier()
;   #define SCHED __builtin_amdgcn_sched_barrier(0)
; template <bool TWO, class MID> ...
;     ...
;     LDB(B0,0,0); SCHED; LDA(At,0,0); STAGE_A(SA(1,1),1,t+1);
;     WAIT_L(8); BAR; WAIT_L(0); MMA(0,0,At,B0); BAR; SCHED;
;     LDB(B1,0,1); STAGE_B(SB(0,0),0,t+2);
;     BAR; WAIT_L(0); MMA(0,1,At,B1); BAR;
;     LDA(At,0,1); STAGE_A(SA(0,0),0,t+2);
;     BAR; WAIT_L(0); MMA(1,0,At,B0); BAR; SCHED;
;     STAGE_B(SB(0,1),1,t+2);
;     WAIT_V(6); BAR; MMA(1,1,At,B1); BAR;
.LBB0_169:
	ds_read_b128 v[170:173], v143
	ds_read_b128 v[174:177], v143 offset:1024
	ds_read_b128 v[178:181], v143 offset:2048
	ds_read_b128 v[182:185], v143 offset:3072
	ds_read_b128 v[186:189], v168
	ds_read_b128 v[190:193], v168 offset:1024
	ds_read_b128 v[196:199], v167
	ds_read_b128 v[200:203], v167 offset:1024
	ds_read_b128 v[204:207], v166
	ds_read_b128 v[208:211], v166 offset:1024
	ds_read_b128 v[212:215], v147
	ds_read_b128 v[216:219], v147 offset:1024
	s_add_u32 s17, s0, s12
	s_addc_u32 s18, s1, s13
	s_add_u32 s20, s17, 0x8080080
	s_addc_u32 s21, s18, 0
	s_add_u32 m0, s98, 0xc000
	global_load_lds_dwordx4 v132, s[20:21]
	s_add_u32 m0, s98, 0xe000
	global_load_lds_dwordx4 v130, s[20:21]
	s_waitcnt lgkmcnt(8)
	s_setprio 1
	s_barrier
	s_waitcnt lgkmcnt(0)
	v_mfma_f32_16x16x32_bf16 v[126:129], v[170:173], v[186:189], v[126:129]
	v_mfma_f32_16x16x32_bf16 v[122:125], v[178:181], v[186:189], v[122:125]
	v_mfma_f32_16x16x32_bf16 v[118:121], v[170:173], v[196:199], v[118:121]
	v_mfma_f32_16x16x32_bf16 v[114:117], v[178:181], v[196:199], v[114:117]
	v_mfma_f32_16x16x32_bf16 v[110:113], v[170:173], v[204:207], v[110:113]
	v_mfma_f32_16x16x32_bf16 v[106:109], v[178:181], v[204:207], v[106:109]
	v_mfma_f32_16x16x32_bf16 v[102:105], v[170:173], v[212:215], v[102:105]
	v_mfma_f32_16x16x32_bf16 v[98:101], v[178:181], v[212:215], v[98:101]
	v_mfma_f32_16x16x32_bf16 v[126:129], v[174:177], v[190:193], v[126:129]
	v_mfma_f32_16x16x32_bf16 v[122:125], v[182:185], v[190:193], v[122:125]
	v_mfma_f32_16x16x32_bf16 v[118:121], v[174:177], v[200:203], v[118:121]
	v_mfma_f32_16x16x32_bf16 v[114:117], v[182:185], v[200:203], v[114:117]
	v_mfma_f32_16x16x32_bf16 v[110:113], v[174:177], v[208:211], v[110:113]
	v_mfma_f32_16x16x32_bf16 v[106:109], v[182:185], v[208:211], v[106:109]
	v_mfma_f32_16x16x32_bf16 v[102:105], v[174:177], v[216:219], v[102:105]
	v_mfma_f32_16x16x32_bf16 v[98:101], v[182:185], v[216:219], v[98:101]
	s_barrier
	s_setprio 0
	s_add_u32 s19, s0, s14
	ds_read_b128 v[220:223], v141
	ds_read_b128 v[224:227], v141 offset:1024
	ds_read_b128 v[228:231], v141 offset:2048
	ds_read_b128 v[232:235], v141 offset:3072
	s_addc_u32 s20, s1, s15
	s_add_u32 s26, s19, 0x100
	s_addc_u32 s27, s20, 0
	s_add_u32 m0, s98, 0x10000
	global_load_lds_dwordx4 v132, s[26:27]
	s_add_u32 m0, s98, 0x12000
	global_load_lds_dwordx4 v130, s[26:27]
	s_setprio 1
	s_barrier
	s_waitcnt lgkmcnt(0)
	v_mfma_f32_16x16x32_bf16 v[94:97], v[220:223], v[186:189], v[94:97]
	v_mfma_f32_16x16x32_bf16 v[90:93], v[228:231], v[186:189], v[90:93]
	v_mfma_f32_16x16x32_bf16 v[86:89], v[220:223], v[196:199], v[86:89]
	v_mfma_f32_16x16x32_bf16 v[82:85], v[228:231], v[196:199], v[82:85]
	v_mfma_f32_16x16x32_bf16 v[78:81], v[220:223], v[204:207], v[78:81]
	v_mfma_f32_16x16x32_bf16 v[74:77], v[228:231], v[204:207], v[74:77]
	v_mfma_f32_16x16x32_bf16 v[70:73], v[220:223], v[212:215], v[70:73]
	v_mfma_f32_16x16x32_bf16 v[66:69], v[228:231], v[212:215], v[66:69]
	v_mfma_f32_16x16x32_bf16 v[94:97], v[224:227], v[190:193], v[94:97]
	v_mfma_f32_16x16x32_bf16 v[90:93], v[232:235], v[190:193], v[90:93]
	v_mfma_f32_16x16x32_bf16 v[86:89], v[224:227], v[200:203], v[86:89]
	v_mfma_f32_16x16x32_bf16 v[82:85], v[232:235], v[200:203], v[82:85]
	v_mfma_f32_16x16x32_bf16 v[78:81], v[224:227], v[208:211], v[78:81]
	v_mfma_f32_16x16x32_bf16 v[74:77], v[232:235], v[208:211], v[74:77]
	v_mfma_f32_16x16x32_bf16 v[70:73], v[224:227], v[216:219], v[70:73]
	v_mfma_f32_16x16x32_bf16 v[66:69], v[232:235], v[216:219], v[66:69]
	s_barrier
	s_setprio 0
	ds_read_b128 v[186:189], v168 offset:16384
	ds_read_b128 v[190:193], v168 offset:17408
	ds_read_b128 v[196:199], v167 offset:16384
	ds_read_b128 v[200:203], v167 offset:17408
	ds_read_b128 v[204:207], v166 offset:16384
	ds_read_b128 v[208:211], v166 offset:17408
	ds_read_b128 v[212:215], v147 offset:16384
	ds_read_b128 v[216:219], v147 offset:17408
	s_add_u32 s26, s17, 0x8000100
	s_addc_u32 s27, s18, 0
	s_add_u32 m0, s98, 0x0
	global_load_lds_dwordx4 v132, s[26:27]
	s_add_u32 m0, s98, 0x2000
	global_load_lds_dwordx4 v130, s[26:27]
	s_setprio 1
	s_barrier
	s_waitcnt lgkmcnt(0)
	v_mfma_f32_16x16x32_bf16 v[62:65], v[170:173], v[186:189], v[62:65]
	v_mfma_f32_16x16x32_bf16 v[58:61], v[178:181], v[186:189], v[58:61]
	v_mfma_f32_16x16x32_bf16 v[54:57], v[170:173], v[196:199], v[54:57]
	v_mfma_f32_16x16x32_bf16 v[50:53], v[178:181], v[196:199], v[50:53]
	v_mfma_f32_16x16x32_bf16 v[46:49], v[170:173], v[204:207], v[46:49]
	v_mfma_f32_16x16x32_bf16 v[42:45], v[178:181], v[204:207], v[42:45]
	v_mfma_f32_16x16x32_bf16 v[38:41], v[170:173], v[212:215], v[38:41]
	v_mfma_f32_16x16x32_bf16 v[34:37], v[178:181], v[212:215], v[34:37]
	v_mfma_f32_16x16x32_bf16 v[62:65], v[174:177], v[190:193], v[62:65]
	v_mfma_f32_16x16x32_bf16 v[58:61], v[182:185], v[190:193], v[58:61]
	v_mfma_f32_16x16x32_bf16 v[54:57], v[174:177], v[200:203], v[54:57]
	v_mfma_f32_16x16x32_bf16 v[50:53], v[182:185], v[200:203], v[50:53]
	v_mfma_f32_16x16x32_bf16 v[46:49], v[174:177], v[208:211], v[46:49]
	v_mfma_f32_16x16x32_bf16 v[42:45], v[182:185], v[208:211], v[42:45]
	v_mfma_f32_16x16x32_bf16 v[38:41], v[174:177], v[216:219], v[38:41]
	v_mfma_f32_16x16x32_bf16 v[34:37], v[182:185], v[216:219], v[34:37]
	s_barrier
	s_setprio 0
	s_add_u32 s26, s19, 0x80100
	s_addc_u32 s27, s20, 0
	s_add_u32 m0, s98, 0x14000
	global_load_lds_dwordx4 v132, s[26:27]
	s_add_u32 m0, s98, 0x16000
	global_load_lds_dwordx4 v130, s[26:27]
	s_waitcnt vmcnt(6)
	s_setprio 1
	s_barrier
;   #define LDA(dst,b,h) for(int m=0;m<4;++m)for(int k=0;k<2;++k) \
;     dst[m][k]=*reinterpret_cast<const bf16x8*>((char*)SA(b,h)+lds_byte(wr*64+m*16+fr,k*32+fq*8))
;   #define LDB(dst,b,h) for(int n=0;n<2;++n)for(int k=0;k<2;++k) \
;     dst[n][k]=*reinterpret_cast<const bf16x8*>((char*)SB(b,h)+lds_byte(wc*32+n*16+fr,k*32+fq*8))
;   #define MMA(ai,bj,At,Bt_) do{__builtin_amdgcn_s_setprio(1); \
;     for(int m=0;m<4;++m)for(int n=0;n<2;++n)for(int k=0;k<2;++k) \
;       acc[ai][bj][m][n]=__builtin_amdgcn_mfma_f32_16x16x32_bf16(Bt_[n][k],At[m][k],acc[ai][bj][m][n],0,0,0); \
;     __builtin_amdgcn_s_setprio(0);}while(0)
;   #define WAIT_V(n) asm volatile("s_waitcnt vmcnt(" #n ")":::"memory")
;   #define WAIT_L(n) asm volatile("s_waitcnt lgkmcnt(" #n ")":::"memory")
;   #define BAR __builtin_amdgcn_s_barrier()
;   #define SCHED __builtin_amdgcn_sched_barrier(0)
; template <bool TWO, class MID> ...
;     ...
;     WAIT_V(6); BAR; MMA(1,1,At,B1); BAR;
;     LDB(B0,1,0); SCHED; LDA(At,1,0); STAGE_A(SA(0,1),1,t+2);
;     WAIT_L(8); BAR; WAIT_L(0); MMA(0,0,At,B0); BAR; SCHED;
;     LDB(B1,1,1); STAGE_B(SB(1,0),0,t+3);
;     BAR; WAIT_L(0); MMA(0,1,At,B1); BAR;
;     LDA(At,1,1); STAGE_A(SA(1,0),0,t+3);
;     BAR; WAIT_L(0); MMA(1,0,At,B0); BAR; SCHED;
	v_mfma_f32_16x16x32_bf16 v[30:33], v[220:223], v[186:189], v[30:33]
	v_mfma_f32_16x16x32_bf16 v[26:29], v[228:231], v[186:189], v[26:29]
	v_mfma_f32_16x16x32_bf16 v[22:25], v[220:223], v[196:199], v[22:25]
	v_mfma_f32_16x16x32_bf16 v[18:21], v[228:231], v[196:199], v[18:21]
	v_mfma_f32_16x16x32_bf16 v[14:17], v[220:223], v[204:207], v[14:17]
	v_mfma_f32_16x16x32_bf16 v[10:13], v[228:231], v[204:207], v[10:13]
	v_mfma_f32_16x16x32_bf16 v[6:9], v[220:223], v[212:215], v[6:9]
	v_mfma_f32_16x16x32_bf16 v[2:5], v[228:231], v[212:215], v[2:5]
	v_mfma_f32_16x16x32_bf16 v[30:33], v[224:227], v[190:193], v[30:33]
	v_mfma_f32_16x16x32_bf16 v[26:29], v[232:235], v[190:193], v[26:29]
	v_mfma_f32_16x16x32_bf16 v[22:25], v[224:227], v[200:203], v[22:25]
	v_mfma_f32_16x16x32_bf16 v[18:21], v[232:235], v[200:203], v[18:21]
	v_mfma_f32_16x16x32_bf16 v[14:17], v[224:227], v[208:211], v[14:17]
	v_mfma_f32_16x16x32_bf16 v[10:13], v[232:235], v[208:211], v[10:13]
	v_mfma_f32_16x16x32_bf16 v[6:9], v[224:227], v[216:219], v[6:9]
	v_mfma_f32_16x16x32_bf16 v[2:5], v[232:235], v[216:219], v[2:5]
	s_barrier
	s_setprio 0
	ds_read_b128 v[170:173], v137
	ds_read_b128 v[174:177], v137 offset:1024
	ds_read_b128 v[178:181], v137 offset:2048
	ds_read_b128 v[182:185], v137 offset:3072
	ds_read_b128 v[186:189], v168 offset:32768
	ds_read_b128 v[190:193], v168 offset:33792
	ds_read_b128 v[196:199], v167 offset:32768
	ds_read_b128 v[200:203], v167 offset:33792
	ds_read_b128 v[204:207], v166 offset:32768
	ds_read_b128 v[208:211], v166 offset:33792
	ds_read_b128 v[212:215], v147 offset:32768
	ds_read_b128 v[216:219], v147 offset:33792
	s_add_u32 s26, s17, 0x8080100
	s_addc_u32 s27, s18, 0
	s_add_u32 m0, s98, 0x4000
	global_load_lds_dwordx4 v132, s[26:27]
	s_add_u32 m0, s98, 0x6000
	global_load_lds_dwordx4 v130, s[26:27]
	s_waitcnt lgkmcnt(8)
	s_setprio 1
	s_barrier
	s_waitcnt lgkmcnt(0)
	v_mfma_f32_16x16x32_bf16 v[126:129], v[170:173], v[186:189], v[126:129]
	v_mfma_f32_16x16x32_bf16 v[122:125], v[178:181], v[186:189], v[122:125]
	v_mfma_f32_16x16x32_bf16 v[118:121], v[170:173], v[196:199], v[118:121]
	v_mfma_f32_16x16x32_bf16 v[114:117], v[178:181], v[196:199], v[114:117]
	v_mfma_f32_16x16x32_bf16 v[110:113], v[170:173], v[204:207], v[110:113]
	v_mfma_f32_16x16x32_bf16 v[106:109], v[178:181], v[204:207], v[106:109]
	v_mfma_f32_16x16x32_bf16 v[102:105], v[170:173], v[212:215], v[102:105]
	v_mfma_f32_16x16x32_bf16 v[98:101], v[178:181], v[212:215], v[98:101]
	v_mfma_f32_16x16x32_bf16 v[126:129], v[174:177], v[190:193], v[126:129]
	v_mfma_f32_16x16x32_bf16 v[122:125], v[182:185], v[190:193], v[122:125]
	v_mfma_f32_16x16x32_bf16 v[118:121], v[174:177], v[200:203], v[118:121]
	v_mfma_f32_16x16x32_bf16 v[114:117], v[182:185], v[200:203], v[114:117]
	v_mfma_f32_16x16x32_bf16 v[110:113], v[174:177], v[208:211], v[110:113]
	v_mfma_f32_16x16x32_bf16 v[106:109], v[182:185], v[208:211], v[106:109]
	v_mfma_f32_16x16x32_bf16 v[102:105], v[174:177], v[216:219], v[102:105]
	v_mfma_f32_16x16x32_bf16 v[98:101], v[182:185], v[216:219], v[98:101]
	s_barrier
	s_setprio 0
	ds_read_b128 v[220:223], v135
	ds_read_b128 v[224:227], v135 offset:1024
	ds_read_b128 v[228:231], v135 offset:2048
	ds_read_b128 v[232:235], v135 offset:3072
	s_add_u32 s26, s19, 0x180
	s_addc_u32 s27, s20, 0
	s_add_u32 m0, s98, 0x18000
	global_load_lds_dwordx4 v132, s[26:27]
	s_add_u32 m0, s98, 0x1a000
	global_load_lds_dwordx4 v130, s[26:27]
	s_setprio 1
	s_barrier
	s_waitcnt lgkmcnt(0)
	v_mfma_f32_16x16x32_bf16 v[94:97], v[220:223], v[186:189], v[94:97]
	v_mfma_f32_16x16x32_bf16 v[90:93], v[228:231], v[186:189], v[90:93]
	v_mfma_f32_16x16x32_bf16 v[86:89], v[220:223], v[196:199], v[86:89]
	v_mfma_f32_16x16x32_bf16 v[82:85], v[228:231], v[196:199], v[82:85]
	v_mfma_f32_16x16x32_bf16 v[78:81], v[220:223], v[204:207], v[78:81]
	v_mfma_f32_16x16x32_bf16 v[74:77], v[228:231], v[204:207], v[74:77]
	v_mfma_f32_16x16x32_bf16 v[70:73], v[220:223], v[212:215], v[70:73]
	v_mfma_f32_16x16x32_bf16 v[66:69], v[228:231], v[212:215], v[66:69]
	v_mfma_f32_16x16x32_bf16 v[94:97], v[224:227], v[190:193], v[94:97]
	v_mfma_f32_16x16x32_bf16 v[90:93], v[232:235], v[190:193], v[90:93]
	v_mfma_f32_16x16x32_bf16 v[86:89], v[224:227], v[200:203], v[86:89]
	v_mfma_f32_16x16x32_bf16 v[82:85], v[232:235], v[200:203], v[82:85]
	v_mfma_f32_16x16x32_bf16 v[78:81], v[224:227], v[208:211], v[78:81]
	v_mfma_f32_16x16x32_bf16 v[74:77], v[232:235], v[208:211], v[74:77]
	v_mfma_f32_16x16x32_bf16 v[70:73], v[224:227], v[216:219], v[70:73]
	v_mfma_f32_16x16x32_bf16 v[66:69], v[232:235], v[216:219], v[66:69]
	s_barrier
	s_setprio 0
	ds_read_b128 v[186:189], v168 offset:49152
	ds_read_b128 v[190:193], v168 offset:50176
	ds_read_b128 v[196:199], v167 offset:49152
	ds_read_b128 v[200:203], v167 offset:50176
	ds_read_b128 v[204:207], v166 offset:49152
	ds_read_b128 v[208:211], v166 offset:50176
	ds_read_b128 v[212:215], v147 offset:49152
	ds_read_b128 v[216:219], v147 offset:50176
	s_add_u32 s26, s17, 0x8000180
	s_addc_u32 s27, s18, 0
	s_add_u32 m0, s98, 0x8000
	global_load_lds_dwordx4 v132, s[26:27]
	s_add_u32 m0, s98, 0xa000
	global_load_lds_dwordx4 v130, s[26:27]
	s_setprio 1
	s_barrier
;   #define LDA(dst,b,h) for(int m=0;m<4;++m)for(int k=0;k<2;++k) \
;     dst[m][k]=*reinterpret_cast<const bf16x8*>((char*)SA(b,h)+lds_byte(wr*64+m*16+fr,k*32+fq*8))
;   #define LDB(dst,b,h) for(int n=0;n<2;++n)for(int k=0;k<2;++k) \
;     dst[n][k]=*reinterpret_cast<const bf16x8*>((char*)SB(b,h)+lds_byte(wc*32+n*16+fr,k*32+fq*8))
;   #define MMA(ai,bj,At,Bt_) do{__builtin_amdgcn_s_setprio(1); \
;     for(int m=0;m<4;++m)for(int n=0;n<2;++n)for(int k=0;k<2;++k) \
;       acc[ai][bj][m][n]=__builtin_amdgcn_mfma_f32_16x16x32_bf16(Bt_[n][k],At[m][k],acc[ai][bj][m][n],0,0,0); \
;     __builtin_amdgcn_s_setprio(0);}while(0)
;   #define WAIT_V(n) asm volatile("s_waitcnt vmcnt(" #n ")":::"memory")
;   #define WAIT_L(n) asm volatile("s_waitcnt lgkmcnt(" #n ")":::"memory")
;   #define BAR __builtin_amdgcn_s_barrier()
;   #define SCHED __builtin_amdgcn_sched_barrier(0)
; template <bool TWO, class MID> ...
;     ...
;     BAR; WAIT_L(0); MMA(1,0,At,B0); BAR; SCHED;
;     STAGE_B(SB(1,1),1,t+3);
;     WAIT_V(6); BAR; MMA(1,1,At,B1); BAR;
;   }
;   { LDB(B0,0,0); LDA(At,0,0); STAGE_A(SA(1,1),1,nt-1);
;     BAR; WAIT_L(0); MMA(0,0,At,B0); BAR;
;     LDB(B1,0,1); BAR; WAIT_L(0); MMA(0,1,At,B1); BAR;
	s_waitcnt lgkmcnt(0)
	v_mfma_f32_16x16x32_bf16 v[62:65], v[170:173], v[186:189], v[62:65]
	v_mfma_f32_16x16x32_bf16 v[58:61], v[178:181], v[186:189], v[58:61]
	v_mfma_f32_16x16x32_bf16 v[54:57], v[170:173], v[196:199], v[54:57]
	v_mfma_f32_16x16x32_bf16 v[50:53], v[178:181], v[196:199], v[50:53]
	v_mfma_f32_16x16x32_bf16 v[46:49], v[170:173], v[204:207], v[46:49]
	v_mfma_f32_16x16x32_bf16 v[42:45], v[178:181], v[204:207], v[42:45]
	v_mfma_f32_16x16x32_bf16 v[38:41], v[170:173], v[212:215], v[38:41]
	v_mfma_f32_16x16x32_bf16 v[34:37], v[178:181], v[212:215], v[34:37]
	v_mfma_f32_16x16x32_bf16 v[62:65], v[174:177], v[190:193], v[62:65]
	v_mfma_f32_16x16x32_bf16 v[58:61], v[182:185], v[190:193], v[58:61]
	v_mfma_f32_16x16x32_bf16 v[54:57], v[174:177], v[200:203], v[54:57]
	v_mfma_f32_16x16x32_bf16 v[50:53], v[182:185], v[200:203], v[50:53]
	v_mfma_f32_16x16x32_bf16 v[46:49], v[174:177], v[208:211], v[46:49]
	v_mfma_f32_16x16x32_bf16 v[42:45], v[182:185], v[208:211], v[42:45]
	v_mfma_f32_16x16x32_bf16 v[38:41], v[174:177], v[216:219], v[38:41]
	v_mfma_f32_16x16x32_bf16 v[34:37], v[182:185], v[216:219], v[34:37]
	s_barrier
	s_setprio 0
	s_add_u32 s18, s19, 0x80180
	s_addc_u32 s19, s20, 0
	s_add_u32 m0, s98, 0x1c000
	global_load_lds_dwordx4 v132, s[18:19]
	s_add_u32 m0, s98, 0x1e000
	global_load_lds_dwordx4 v130, s[18:19]
	s_waitcnt vmcnt(6)
	s_setprio 1
	s_barrier
	v_mfma_f32_16x16x32_bf16 v[30:33], v[220:223], v[186:189], v[30:33]
	v_mfma_f32_16x16x32_bf16 v[26:29], v[228:231], v[186:189], v[26:29]
	v_mfma_f32_16x16x32_bf16 v[22:25], v[220:223], v[196:199], v[22:25]
	v_mfma_f32_16x16x32_bf16 v[18:21], v[228:231], v[196:199], v[18:21]
	v_mfma_f32_16x16x32_bf16 v[14:17], v[220:223], v[204:207], v[14:17]
	v_mfma_f32_16x16x32_bf16 v[10:13], v[228:231], v[204:207], v[10:13]
	v_mfma_f32_16x16x32_bf16 v[6:9], v[220:223], v[212:215], v[6:9]
	v_mfma_f32_16x16x32_bf16 v[2:5], v[228:231], v[212:215], v[2:5]
	v_mfma_f32_16x16x32_bf16 v[30:33], v[224:227], v[190:193], v[30:33]
	v_mfma_f32_16x16x32_bf16 v[26:29], v[232:235], v[190:193], v[26:29]
	v_mfma_f32_16x16x32_bf16 v[22:25], v[224:227], v[200:203], v[22:25]
	v_mfma_f32_16x16x32_bf16 v[18:21], v[232:235], v[200:203], v[18:21]
	v_mfma_f32_16x16x32_bf16 v[14:17], v[224:227], v[208:211], v[14:17]
	v_mfma_f32_16x16x32_bf16 v[10:13], v[232:235], v[208:211], v[10:13]
	v_mfma_f32_16x16x32_bf16 v[6:9], v[224:227], v[216:219], v[6:9]
	v_mfma_f32_16x16x32_bf16 v[2:5], v[232:235], v[216:219], v[2:5]
	s_setprio 0
	s_add_i32 s9, s9, 2
	s_add_u32 s0, s0, 0x100
	s_addc_u32 s1, s1, 0
	s_cmp_lt_u32 s9, 28
	s_barrier
	s_cbranch_scc1 .LBB0_169
	ds_read_b128 v[150:153], v143
	ds_read_b128 v[158:161], v143 offset:1024
	ds_read_b128 v[162:165], v143 offset:2048
	ds_read_b128 v[142:145], v143 offset:3072
	ds_read_b128 v[170:173], v168
	ds_read_b128 v[174:177], v168 offset:1024
	ds_read_b128 v[178:181], v167
	ds_read_b128 v[182:185], v167 offset:1024
	ds_read_b128 v[186:189], v166
	ds_read_b128 v[190:193], v166 offset:1024
	ds_read_b128 v[196:199], v147
	ds_read_b128 v[200:203], v147 offset:1024
	s_add_u32 s0, s11, 0x80f80
	s_addc_u32 s1, s16, 0
	v_lshl_add_u64 v[132:133], s[0:1], 0, v[132:133]
	v_readfirstlane_b32 s9, v148
	s_mov_b32 m0, s9
	global_load_lds_dwordx4 v[132:133], off
	v_lshl_add_u64 v[130:131], s[0:1], 0, v[130:131]
	v_readfirstlane_b32 s0, v156
	s_mov_b32 m0, s0
	global_load_lds_dwordx4 v[130:131], off
	s_setprio 1
	s_barrier
	s_waitcnt lgkmcnt(0)
	v_mfma_f32_16x16x32_bf16 v[126:129], v[150:153], v[170:173], v[126:129]
	v_mfma_f32_16x16x32_bf16 v[122:125], v[162:165], v[170:173], v[122:125]
	v_mfma_f32_16x16x32_bf16 v[114:117], v[162:165], v[178:181], v[114:117]
	v_mfma_f32_16x16x32_bf16 v[106:109], v[162:165], v[186:189], v[106:109]
	v_mfma_f32_16x16x32_bf16 v[98:101], v[162:165], v[196:199], v[98:101]
	v_mfma_f32_16x16x32_bf16 v[126:129], v[158:161], v[174:177], v[126:129]
	v_mfma_f32_16x16x32_bf16 v[122:125], v[142:145], v[174:177], v[122:125]
	v_mfma_f32_16x16x32_bf16 v[118:121], v[150:153], v[178:181], v[118:121]
	v_mfma_f32_16x16x32_bf16 v[114:117], v[142:145], v[182:185], v[114:117]
	v_mfma_f32_16x16x32_bf16 v[110:113], v[150:153], v[186:189], v[110:113]
	v_mfma_f32_16x16x32_bf16 v[106:109], v[142:145], v[190:193], v[106:109]
	v_mfma_f32_16x16x32_bf16 v[102:105], v[150:153], v[196:199], v[102:105]
	v_mfma_f32_16x16x32_bf16 v[130:133], v[142:145], v[200:203], v[98:101]
	v_mfma_f32_16x16x32_bf16 v[118:121], v[158:161], v[182:185], v[118:121]
	v_mfma_f32_16x16x32_bf16 v[110:113], v[158:161], v[190:193], v[110:113]
	v_mfma_f32_16x16x32_bf16 v[102:105], v[158:161], v[200:203], v[102:105]
	s_barrier
	s_setprio 0
	ds_read_b128 v[98:101], v141
	ds_read_b128 v[154:157], v141 offset:1024
	ds_read_b128 v[204:207], v141 offset:2048
	ds_read_b128 v[138:141], v141 offset:3072
	s_setprio 1
	s_barrier
	s_waitcnt lgkmcnt(0)
	v_mfma_f32_16x16x32_bf16 v[86:89], v[98:101], v[178:181], v[86:89]
	v_mfma_f32_16x16x32_bf16 v[82:85], v[204:207], v[178:181], v[82:85]
	v_mfma_f32_16x16x32_bf16 v[70:73], v[98:101], v[196:199], v[70:73]
	v_mfma_f32_16x16x32_bf16 v[66:69], v[204:207], v[196:199], v[66:69]
	v_mfma_f32_16x16x32_bf16 v[94:97], v[98:101], v[170:173], v[94:97]
	v_mfma_f32_16x16x32_bf16 v[90:93], v[204:207], v[170:173], v[90:93]
	v_mfma_f32_16x16x32_bf16 v[86:89], v[154:157], v[182:185], v[86:89]
	v_mfma_f32_16x16x32_bf16 v[82:85], v[138:141], v[182:185], v[82:85]
	v_mfma_f32_16x16x32_bf16 v[78:81], v[98:101], v[186:189], v[78:81]
	v_mfma_f32_16x16x32_bf16 v[74:77], v[204:207], v[186:189], v[74:77]
	v_mfma_f32_16x16x32_bf16 v[70:73], v[154:157], v[200:203], v[70:73]
	v_mfma_f32_16x16x32_bf16 v[66:69], v[138:141], v[200:203], v[66:69]
	v_mfma_f32_16x16x32_bf16 v[94:97], v[154:157], v[174:177], v[94:97]
	v_mfma_f32_16x16x32_bf16 v[170:173], v[138:141], v[174:177], v[90:93]
	v_mfma_f32_16x16x32_bf16 v[174:177], v[154:157], v[190:193], v[78:81]
	v_mfma_f32_16x16x32_bf16 v[178:181], v[138:141], v[190:193], v[74:77]
	s_barrier
;   #define LDA(dst,b,h) for(int m=0;m<4;++m)for(int k=0;k<2;++k) \
;     dst[m][k]=*reinterpret_cast<const bf16x8*>((char*)SA(b,h)+lds_byte(wr*64+m*16+fr,k*32+fq*8))
;   #define LDB(dst,b,h) for(int n=0;n<2;++n)for(int k=0;k<2;++k) \
;     dst[n][k]=*reinterpret_cast<const bf16x8*>((char*)SB(b,h)+lds_byte(wc*32+n*16+fr,k*32+fq*8))
;   #define MMA(ai,bj,At,Bt_) do{__builtin_amdgcn_s_setprio(1); \
;     for(int m=0;m<4;++m)for(int n=0;n<2;++n)for(int k=0;k<2;++k) \
;       acc[ai][bj][m][n]=__builtin_amdgcn_mfma_f32_16x16x32_bf16(Bt_[n][k],At[m][k],acc[ai][bj][m][n],0,0,0); \
;     __builtin_amdgcn_s_setprio(0);}while(0)
;   #define WAIT_V(n) asm volatile("s_waitcnt vmcnt(" #n ")":::"memory")
;   #define WAIT_L(n) asm volatile("s_waitcnt lgkmcnt(" #n ")":::"memory")
;   #define BAR __builtin_amdgcn_s_barrier()
; template <bool TWO, class MID> ...
;     ...
;     LDA(At,0,1); WAIT_V(4); BAR; WAIT_L(0); MMA(1,0,At,B0); MMA(1,1,At,B1); BAR; }
;   { LDB(B0,1,0); LDA(At,1,0); WAIT_V(2); BAR; WAIT_L(0); MMA(0,0,At,B0); BAR;
	s_setprio 0
	s_nop 0
	ds_read_b128 v[74:77], v168 offset:16384
	ds_read_b128 v[78:81], v168 offset:17408
	ds_read_b128 v[90:93], v167 offset:16384
	ds_read_b128 v[182:185], v167 offset:17408
	ds_read_b128 v[186:189], v166 offset:16384
	ds_read_b128 v[190:193], v166 offset:17408
	ds_read_b128 v[196:199], v147 offset:16384
	ds_read_b128 v[200:203], v147 offset:17408
	s_waitcnt vmcnt(4)
	s_setprio 1
	s_barrier
	s_waitcnt lgkmcnt(0)
	v_mfma_f32_16x16x32_bf16 v[62:65], v[150:153], v[74:77], v[62:65]
	v_mfma_f32_16x16x32_bf16 v[58:61], v[162:165], v[74:77], v[58:61]
	v_mfma_f32_16x16x32_bf16 v[54:57], v[150:153], v[90:93], v[54:57]
	v_mfma_f32_16x16x32_bf16 v[50:53], v[162:165], v[90:93], v[50:53]
	v_mfma_f32_16x16x32_bf16 v[38:41], v[150:153], v[196:199], v[38:41]
	v_mfma_f32_16x16x32_bf16 v[34:37], v[162:165], v[196:199], v[34:37]
	v_mfma_f32_16x16x32_bf16 v[62:65], v[158:161], v[78:81], v[62:65]
	v_mfma_f32_16x16x32_bf16 v[58:61], v[142:145], v[78:81], v[58:61]
	v_mfma_f32_16x16x32_bf16 v[54:57], v[158:161], v[182:185], v[54:57]
	v_mfma_f32_16x16x32_bf16 v[50:53], v[142:145], v[182:185], v[50:53]
	v_mfma_f32_16x16x32_bf16 v[46:49], v[150:153], v[186:189], v[46:49]
	v_mfma_f32_16x16x32_bf16 v[42:45], v[162:165], v[186:189], v[42:45]
	v_mfma_f32_16x16x32_bf16 v[38:41], v[158:161], v[200:203], v[38:41]
	v_mfma_f32_16x16x32_bf16 v[34:37], v[142:145], v[200:203], v[34:37]
	v_mfma_f32_16x16x32_bf16 v[208:211], v[158:161], v[190:193], v[46:49]
	v_mfma_f32_16x16x32_bf16 v[212:215], v[142:145], v[190:193], v[42:45]
	s_setprio 0
	s_setprio 1
	v_mfma_f32_16x16x32_bf16 v[22:25], v[98:101], v[90:93], v[22:25]
	v_mfma_f32_16x16x32_bf16 v[18:21], v[204:207], v[90:93], v[18:21]
	v_mfma_f32_16x16x32_bf16 v[6:9], v[98:101], v[196:199], v[6:9]
	v_mfma_f32_16x16x32_bf16 v[2:5], v[204:207], v[196:199], v[2:5]
	v_mfma_f32_16x16x32_bf16 v[30:33], v[98:101], v[74:77], v[30:33]
	v_mfma_f32_16x16x32_bf16 v[26:29], v[204:207], v[74:77], v[26:29]
	v_mfma_f32_16x16x32_bf16 v[22:25], v[154:157], v[182:185], v[22:25]
	v_mfma_f32_16x16x32_bf16 v[18:21], v[138:141], v[182:185], v[18:21]
	v_mfma_f32_16x16x32_bf16 v[14:17], v[98:101], v[186:189], v[14:17]
	v_mfma_f32_16x16x32_bf16 v[10:13], v[204:207], v[186:189], v[10:13]
	v_mfma_f32_16x16x32_bf16 v[6:9], v[154:157], v[200:203], v[6:9]
	v_mfma_f32_16x16x32_bf16 v[2:5], v[138:141], v[200:203], v[2:5]
	v_mfma_f32_16x16x32_bf16 v[148:151], v[154:157], v[78:81], v[30:33]
	v_mfma_f32_16x16x32_bf16 v[158:161], v[138:141], v[78:81], v[26:29]
	v_mfma_f32_16x16x32_bf16 v[162:165], v[154:157], v[190:193], v[14:17]
	v_mfma_f32_16x16x32_bf16 v[182:185], v[138:141], v[190:193], v[10:13]
	s_barrier
	s_setprio 0
	s_nop 0
	ds_read_b128 v[10:13], v137
	ds_read_b128 v[14:17], v137 offset:1024
	ds_read_b128 v[152:155], v137 offset:2048
	ds_read_b128 v[186:189], v137 offset:3072
	ds_read_b128 v[26:29], v168 offset:32768
	ds_read_b128 v[30:33], v168 offset:33792
	ds_read_b128 v[42:45], v167 offset:32768
	ds_read_b128 v[46:49], v167 offset:33792
	ds_read_b128 v[190:193], v166 offset:32768
	ds_read_b128 v[196:199], v166 offset:33792
	ds_read_b128 v[200:203], v147 offset:32768
	ds_read_b128 v[204:207], v147 offset:33792
	s_waitcnt vmcnt(2)
	s_setprio 1
	s_barrier
	s_waitcnt lgkmcnt(0)
	v_mfma_f32_16x16x32_bf16 v[74:77], v[10:13], v[26:29], v[126:129]
	v_mfma_f32_16x16x32_bf16 v[142:145], v[14:17], v[30:33], v[74:77]
	v_mfma_f32_16x16x32_bf16 v[74:77], v[152:155], v[26:29], v[122:125]
	v_mfma_f32_16x16x32_bf16 v[138:141], v[186:189], v[30:33], v[74:77]
	v_mfma_f32_16x16x32_bf16 v[74:77], v[10:13], v[42:45], v[118:121]
	v_mfma_f32_16x16x32_bf16 v[126:129], v[14:17], v[46:49], v[74:77]
	v_mfma_f32_16x16x32_bf16 v[74:77], v[152:155], v[42:45], v[114:117]
	v_mfma_f32_16x16x32_bf16 v[122:125], v[186:189], v[46:49], v[74:77]
	v_mfma_f32_16x16x32_bf16 v[74:77], v[10:13], v[190:193], v[110:113]
	v_mfma_f32_16x16x32_bf16 v[98:101], v[14:17], v[196:199], v[74:77]
	v_mfma_f32_16x16x32_bf16 v[74:77], v[152:155], v[190:193], v[106:109]
	v_mfma_f32_16x16x32_bf16 v[90:93], v[186:189], v[196:199], v[74:77]
	v_mfma_f32_16x16x32_bf16 v[74:77], v[10:13], v[200:203], v[102:105]
	v_mfma_f32_16x16x32_bf16 v[78:81], v[14:17], v[204:207], v[74:77]
	v_mfma_f32_16x16x32_bf16 v[74:77], v[152:155], v[200:203], v[130:133]
	v_mfma_f32_16x16x32_bf16 v[74:77], v[186:189], v[204:207], v[74:77]
	s_barrier
;   #define LDA(dst,b,h) for(int m=0;m<4;++m)for(int k=0;k<2;++k) \
;     dst[m][k]=*reinterpret_cast<const bf16x8*>((char*)SA(b,h)+lds_byte(wr*64+m*16+fr,k*32+fq*8))
;   #define LDB(dst,b,h) for(int n=0;n<2;++n)for(int k=0;k<2;++k) \
;     dst[n][k]=*reinterpret_cast<const bf16x8*>((char*)SB(b,h)+lds_byte(wc*32+n*16+fr,k*32+fq*8))
;   #define MMA(ai,bj,At,Bt_) do{__builtin_amdgcn_s_setprio(1); \
;     for(int m=0;m<4;++m)for(int n=0;n<2;++n)for(int k=0;k<2;++k) \
;       acc[ai][bj][m][n]=__builtin_amdgcn_mfma_f32_16x16x32_bf16(Bt_[n][k],At[m][k],acc[ai][bj][m][n],0,0,0); \
;     __builtin_amdgcn_s_setprio(0);}while(0)
;   #define WAIT_V(n) asm volatile("s_waitcnt vmcnt(" #n ")":::"memory")
;   #define WAIT_L(n) asm volatile("s_waitcnt lgkmcnt(" #n ")":::"memory")
;   #define BAR __builtin_amdgcn_s_barrier()
; template <bool TWO, class MID> ...
;     ...
;   { LDB(B0,1,0); LDA(At,1,0); WAIT_V(2); BAR; WAIT_L(0); MMA(0,0,At,B0); BAR;
;     LDB(B1,1,1); WAIT_V(0); BAR; WAIT_L(0); MMA(0,1,At,B1); BAR;
;     LDA(At,1,1); BAR; WAIT_L(0); MMA(1,0,At,B0); MMA(1,1,At,B1); BAR; }
;   if(wr==0)BAR;
	s_setprio 0
	ds_read_b128 v[102:105], v135
	ds_read_b128 v[110:113], v135 offset:1024
	ds_read_b128 v[118:121], v135 offset:2048
	ds_read_b128 v[216:219], v135 offset:3072
	s_waitcnt vmcnt(0)
	s_setprio 1
	s_barrier
	s_waitcnt lgkmcnt(0)
	v_mfma_f32_16x16x32_bf16 v[94:97], v[102:105], v[26:29], v[94:97]
	v_mfma_f32_16x16x32_bf16 v[26:29], v[118:121], v[26:29], v[170:173]
	v_mfma_f32_16x16x32_bf16 v[130:133], v[216:219], v[30:33], v[26:29]
	v_mfma_f32_16x16x32_bf16 v[26:29], v[102:105], v[42:45], v[86:89]
	v_mfma_f32_16x16x32_bf16 v[114:117], v[110:113], v[46:49], v[26:29]
	v_mfma_f32_16x16x32_bf16 v[26:29], v[118:121], v[42:45], v[82:85]
	v_mfma_f32_16x16x32_bf16 v[106:109], v[216:219], v[46:49], v[26:29]
	v_mfma_f32_16x16x32_bf16 v[26:29], v[102:105], v[190:193], v[174:177]
	v_mfma_f32_16x16x32_bf16 v[86:89], v[110:113], v[196:199], v[26:29]
	v_mfma_f32_16x16x32_bf16 v[26:29], v[118:121], v[190:193], v[178:181]
	v_mfma_f32_16x16x32_bf16 v[82:85], v[216:219], v[196:199], v[26:29]
	v_mfma_f32_16x16x32_bf16 v[26:29], v[102:105], v[200:203], v[70:73]
	v_mfma_f32_16x16x32_bf16 v[70:73], v[110:113], v[204:207], v[26:29]
	v_mfma_f32_16x16x32_bf16 v[26:29], v[118:121], v[200:203], v[66:69]
	v_mfma_f32_16x16x32_bf16 v[134:137], v[110:113], v[30:33], v[94:97]
	v_mfma_f32_16x16x32_bf16 v[66:69], v[216:219], v[204:207], v[26:29]
	s_barrier
	s_setprio 0
	ds_read_b128 v[94:97], v168 offset:49152
	ds_read_b128 v[168:171], v168 offset:50176
	ds_read_b128 v[172:175], v167 offset:49152
	ds_read_b128 v[176:179], v167 offset:50176
	ds_read_b128 v[190:193], v166 offset:49152
	ds_read_b128 v[196:199], v166 offset:50176
	ds_read_b128 v[200:203], v147 offset:49152
	ds_read_b128 v[204:207], v147 offset:50176
	s_setprio 1
	s_barrier
	s_waitcnt lgkmcnt(0)
	v_mfma_f32_16x16x32_bf16 v[26:29], v[10:13], v[94:97], v[62:65]
	v_mfma_f32_16x16x32_bf16 v[62:65], v[14:17], v[168:171], v[26:29]
	v_mfma_f32_16x16x32_bf16 v[26:29], v[152:155], v[94:97], v[58:61]
	v_mfma_f32_16x16x32_bf16 v[58:61], v[186:189], v[168:171], v[26:29]
	v_mfma_f32_16x16x32_bf16 v[26:29], v[10:13], v[172:175], v[54:57]
	v_mfma_f32_16x16x32_bf16 v[46:49], v[14:17], v[176:179], v[26:29]
	v_mfma_f32_16x16x32_bf16 v[26:29], v[152:155], v[172:175], v[50:53]
	v_mfma_f32_16x16x32_bf16 v[42:45], v[186:189], v[176:179], v[26:29]
	v_mfma_f32_16x16x32_bf16 v[26:29], v[10:13], v[190:193], v[208:211]
	v_mfma_f32_16x16x32_bf16 v[10:13], v[10:13], v[200:203], v[38:41]
	v_mfma_f32_16x16x32_bf16 v[30:33], v[14:17], v[196:199], v[26:29]
	v_mfma_f32_16x16x32_bf16 v[26:29], v[152:155], v[190:193], v[212:215]
	v_mfma_f32_16x16x32_bf16 v[14:17], v[14:17], v[204:207], v[10:13]
	v_mfma_f32_16x16x32_bf16 v[10:13], v[152:155], v[200:203], v[34:37]
	v_mfma_f32_16x16x32_bf16 v[26:29], v[186:189], v[196:199], v[26:29]
	v_mfma_f32_16x16x32_bf16 v[10:13], v[186:189], v[204:207], v[10:13]
	s_setprio 0
	s_setprio 1
	v_mfma_f32_16x16x32_bf16 v[34:37], v[102:105], v[94:97], v[148:151]
	v_mfma_f32_16x16x32_bf16 v[54:57], v[110:113], v[168:171], v[34:37]
	v_mfma_f32_16x16x32_bf16 v[34:37], v[118:121], v[94:97], v[158:161]
	v_mfma_f32_16x16x32_bf16 v[18:21], v[118:121], v[172:175], v[18:21]
	v_mfma_f32_16x16x32_bf16 v[50:53], v[216:219], v[168:171], v[34:37]
	v_mfma_f32_16x16x32_bf16 v[22:25], v[102:105], v[172:175], v[22:25]
	v_mfma_f32_16x16x32_bf16 v[34:37], v[216:219], v[176:179], v[18:21]
	v_mfma_f32_16x16x32_bf16 v[18:21], v[102:105], v[190:193], v[162:165]
	v_mfma_f32_16x16x32_bf16 v[38:41], v[110:113], v[176:179], v[22:25]
	v_mfma_f32_16x16x32_bf16 v[22:25], v[110:113], v[196:199], v[18:21]
	v_mfma_f32_16x16x32_bf16 v[18:21], v[118:121], v[190:193], v[182:185]
	v_mfma_f32_16x16x32_bf16 v[6:9], v[102:105], v[200:203], v[6:9]
	v_mfma_f32_16x16x32_bf16 v[2:5], v[118:121], v[200:203], v[2:5]
	v_mfma_f32_16x16x32_bf16 v[18:21], v[216:219], v[196:199], v[18:21]
	v_mfma_f32_16x16x32_bf16 v[6:9], v[110:113], v[204:207], v[6:9]
	v_mfma_f32_16x16x32_bf16 v[2:5], v[216:219], v[204:207], v[2:5]
	s_setprio 0
	v_cmp_gt_u32_e32 vcc, s30, v1
	s_barrier
	s_and_saveexec_b64 s[0:1], vcc
	s_cbranch_execz .LBB0_172
	s_barrier

;   #define LDA(dst,b,h) for(int m=0;m<4;++m)for(int k=0;k<2;++k) \
;     dst[m][k]=*reinterpret_cast<const bf16x8*>((char*)SA(b,h)+lds_byte(wr*64+m*16+fr,k*32+fq*8))
;   #define LDB(dst,b,h) for(int n=0;n<2;++n)for(int k=0;k<2;++k) \
;     dst[n][k]=*reinterpret_cast<const bf16x8*>((char*)SB(b,h)+lds_byte(wc*32+n*16+fr,k*32+fq*8))
;   #define MMA(ai,bj,At,Bt_) do{__builtin_amdgcn_s_setprio(1); \
;     for(int m=0;m<4;++m)for(int n=0;n<2;++n)for(int k=0;k<2;++k) \
;       acc[ai][bj][m][n]=__builtin_amdgcn_mfma_f32_16x16x32_bf16(Bt_[n][k],At[m][k],acc[ai][bj][m][n],0,0,0); \
;     __builtin_amdgcn_s_setprio(0);}while(0)
;   #define WAIT_V(n) asm volatile("s_waitcnt vmcnt(" #n ")":::"memory")
;   #define WAIT_L(n) asm volatile("s_waitcnt lgkmcnt(" #n ")":::"memory")
;   #define BAR __builtin_amdgcn_s_barrier()
;   #define SCHED __builtin_amdgcn_sched_barrier(0)
; template <bool TWO, class MID> ...
;     ...
;     LDB(B0,0,0); SCHED; LDA(At,0,0); STAGE_A(SA(1,1),1,t+1);
;     WAIT_L(8); BAR; WAIT_L(0); MMA(0,0,At,B0); BAR; SCHED;
;     LDB(B1,0,1); STAGE_B(SB(0,0),0,t+2);
;     BAR; WAIT_L(0); MMA(0,1,At,B1); BAR;
;     LDA(At,0,1); STAGE_A(SA(0,0),0,t+2);
;     BAR; WAIT_L(0); MMA(1,0,At,B0); BAR; SCHED;
;     STAGE_B(SB(0,1),1,t+2);
;     WAIT_V(6); BAR; MMA(1,1,At,B1); BAR;
.LBB0_489:
	ds_read_b128 v[166:169], v149
	ds_read_b128 v[170:173], v149 offset:1024
	ds_read_b128 v[174:177], v149 offset:2048
	ds_read_b128 v[178:181], v149 offset:3072
	ds_read_b128 v[182:185], v141
	ds_read_b128 v[186:189], v141 offset:1024
	ds_read_b128 v[190:193], v139
	ds_read_b128 v[196:199], v139 offset:1024
	ds_read_b128 v[200:203], v137
	ds_read_b128 v[204:207], v137 offset:1024
	ds_read_b128 v[208:211], v135
	ds_read_b128 v[212:215], v135 offset:1024
	s_add_u32 s19, s4, s10
	s_addc_u32 s24, s5, s11
	s_add_u32 s26, s19, 0x36080080
	s_addc_u32 s27, s24, 0
	s_add_u32 m0, s98, 0xc000
	global_load_lds_dwordx4 v132, s[26:27]
	s_add_u32 m0, s98, 0xe000
	global_load_lds_dwordx4 v130, s[26:27]
	s_waitcnt lgkmcnt(8)
	s_setprio 1
	s_barrier
	s_waitcnt lgkmcnt(0)
	v_mfma_f32_16x16x32_bf16 v[126:129], v[166:169], v[182:185], v[126:129]
	v_mfma_f32_16x16x32_bf16 v[122:125], v[174:177], v[182:185], v[122:125]
	v_mfma_f32_16x16x32_bf16 v[118:121], v[166:169], v[190:193], v[118:121]
	v_mfma_f32_16x16x32_bf16 v[114:117], v[174:177], v[190:193], v[114:117]
	v_mfma_f32_16x16x32_bf16 v[110:113], v[166:169], v[200:203], v[110:113]
	v_mfma_f32_16x16x32_bf16 v[106:109], v[174:177], v[200:203], v[106:109]
	v_mfma_f32_16x16x32_bf16 v[102:105], v[166:169], v[208:211], v[102:105]
	v_mfma_f32_16x16x32_bf16 v[98:101], v[174:177], v[208:211], v[98:101]
	v_mfma_f32_16x16x32_bf16 v[126:129], v[170:173], v[186:189], v[126:129]
	v_mfma_f32_16x16x32_bf16 v[122:125], v[178:181], v[186:189], v[122:125]
	v_mfma_f32_16x16x32_bf16 v[118:121], v[170:173], v[196:199], v[118:121]
	v_mfma_f32_16x16x32_bf16 v[114:117], v[178:181], v[196:199], v[114:117]
	v_mfma_f32_16x16x32_bf16 v[110:113], v[170:173], v[204:207], v[110:113]
	v_mfma_f32_16x16x32_bf16 v[106:109], v[178:181], v[204:207], v[106:109]
	v_mfma_f32_16x16x32_bf16 v[102:105], v[170:173], v[212:215], v[102:105]
	v_mfma_f32_16x16x32_bf16 v[98:101], v[178:181], v[212:215], v[98:101]
	s_barrier
	s_setprio 0
	s_add_u32 s25, s4, s16
	ds_read_b128 v[216:219], v147
	ds_read_b128 v[220:223], v147 offset:1024
	ds_read_b128 v[224:227], v147 offset:2048
	ds_read_b128 v[228:231], v147 offset:3072
	s_addc_u32 s26, s5, s17
	s_add_u32 s28, s25, 0x3400100
	s_addc_u32 s29, s26, 0
	s_add_u32 m0, s98, 0x10000
	global_load_lds_dwordx4 v132, s[28:29]
	s_add_u32 m0, s98, 0x12000
	global_load_lds_dwordx4 v130, s[28:29]
	s_setprio 1
	s_barrier
	s_waitcnt lgkmcnt(0)
	v_mfma_f32_16x16x32_bf16 v[94:97], v[216:219], v[182:185], v[94:97]
	v_mfma_f32_16x16x32_bf16 v[90:93], v[224:227], v[182:185], v[90:93]
	v_mfma_f32_16x16x32_bf16 v[86:89], v[216:219], v[190:193], v[86:89]
	v_mfma_f32_16x16x32_bf16 v[82:85], v[224:227], v[190:193], v[82:85]
	v_mfma_f32_16x16x32_bf16 v[78:81], v[216:219], v[200:203], v[78:81]
	v_mfma_f32_16x16x32_bf16 v[74:77], v[224:227], v[200:203], v[74:77]
	v_mfma_f32_16x16x32_bf16 v[70:73], v[216:219], v[208:211], v[70:73]
	v_mfma_f32_16x16x32_bf16 v[66:69], v[224:227], v[208:211], v[66:69]
	v_mfma_f32_16x16x32_bf16 v[94:97], v[220:223], v[186:189], v[94:97]
	v_mfma_f32_16x16x32_bf16 v[90:93], v[228:231], v[186:189], v[90:93]
	v_mfma_f32_16x16x32_bf16 v[86:89], v[220:223], v[196:199], v[86:89]
	v_mfma_f32_16x16x32_bf16 v[82:85], v[228:231], v[196:199], v[82:85]
	v_mfma_f32_16x16x32_bf16 v[78:81], v[220:223], v[204:207], v[78:81]
	v_mfma_f32_16x16x32_bf16 v[74:77], v[228:231], v[204:207], v[74:77]
	v_mfma_f32_16x16x32_bf16 v[70:73], v[220:223], v[212:215], v[70:73]
	v_mfma_f32_16x16x32_bf16 v[66:69], v[228:231], v[212:215], v[66:69]
	s_barrier
	s_setprio 0
	ds_read_b128 v[182:185], v141 offset:16384
	ds_read_b128 v[186:189], v141 offset:17408
	ds_read_b128 v[190:193], v139 offset:16384
	ds_read_b128 v[196:199], v139 offset:17408
	ds_read_b128 v[200:203], v137 offset:16384
	ds_read_b128 v[204:207], v137 offset:17408
	ds_read_b128 v[208:211], v135 offset:16384
	ds_read_b128 v[212:215], v135 offset:17408
	s_add_u32 s28, s19, 0x36000100
	s_addc_u32 s29, s24, 0
	s_add_u32 m0, s98, 0x0
	global_load_lds_dwordx4 v132, s[28:29]
	s_add_u32 m0, s98, 0x2000
	global_load_lds_dwordx4 v130, s[28:29]
	s_setprio 1
	s_barrier
	s_waitcnt lgkmcnt(0)
	v_mfma_f32_16x16x32_bf16 v[62:65], v[166:169], v[182:185], v[62:65]
	v_mfma_f32_16x16x32_bf16 v[58:61], v[174:177], v[182:185], v[58:61]
	v_mfma_f32_16x16x32_bf16 v[54:57], v[166:169], v[190:193], v[54:57]
	v_mfma_f32_16x16x32_bf16 v[50:53], v[174:177], v[190:193], v[50:53]
	v_mfma_f32_16x16x32_bf16 v[46:49], v[166:169], v[200:203], v[46:49]
	v_mfma_f32_16x16x32_bf16 v[42:45], v[174:177], v[200:203], v[42:45]
	v_mfma_f32_16x16x32_bf16 v[38:41], v[166:169], v[208:211], v[38:41]
	v_mfma_f32_16x16x32_bf16 v[34:37], v[174:177], v[208:211], v[34:37]
	v_mfma_f32_16x16x32_bf16 v[62:65], v[170:173], v[186:189], v[62:65]
	v_mfma_f32_16x16x32_bf16 v[58:61], v[178:181], v[186:189], v[58:61]
	v_mfma_f32_16x16x32_bf16 v[54:57], v[170:173], v[196:199], v[54:57]
	v_mfma_f32_16x16x32_bf16 v[50:53], v[178:181], v[196:199], v[50:53]
	v_mfma_f32_16x16x32_bf16 v[46:49], v[170:173], v[204:207], v[46:49]
	v_mfma_f32_16x16x32_bf16 v[42:45], v[178:181], v[204:207], v[42:45]
	v_mfma_f32_16x16x32_bf16 v[38:41], v[170:173], v[212:215], v[38:41]
	v_mfma_f32_16x16x32_bf16 v[34:37], v[178:181], v[212:215], v[34:37]
	s_barrier
	s_setprio 0
	s_add_u32 s28, s25, 0x3480100
	s_addc_u32 s29, s26, 0
	s_add_u32 m0, s98, 0x14000
	global_load_lds_dwordx4 v132, s[28:29]
	s_add_u32 m0, s98, 0x16000
	global_load_lds_dwordx4 v130, s[28:29]
	s_waitcnt vmcnt(6)
	s_setprio 1
	s_barrier
;   #define LDA(dst,b,h) for(int m=0;m<4;++m)for(int k=0;k<2;++k) \
;     dst[m][k]=*reinterpret_cast<const bf16x8*>((char*)SA(b,h)+lds_byte(wr*64+m*16+fr,k*32+fq*8))
;   #define LDB(dst,b,h) for(int n=0;n<2;++n)for(int k=0;k<2;++k) \
;     dst[n][k]=*reinterpret_cast<const bf16x8*>((char*)SB(b,h)+lds_byte(wc*32+n*16+fr,k*32+fq*8))
;   #define MMA(ai,bj,At,Bt_) do{__builtin_amdgcn_s_setprio(1); \
;     for(int m=0;m<4;++m)for(int n=0;n<2;++n)for(int k=0;k<2;++k) \
;       acc[ai][bj][m][n]=__builtin_amdgcn_mfma_f32_16x16x32_bf16(Bt_[n][k],At[m][k],acc[ai][bj][m][n],0,0,0); \
;     __builtin_amdgcn_s_setprio(0);}while(0)
;   #define WAIT_V(n) asm volatile("s_waitcnt vmcnt(" #n ")":::"memory")
;   #define WAIT_L(n) asm volatile("s_waitcnt lgkmcnt(" #n ")":::"memory")
;   #define BAR __builtin_amdgcn_s_barrier()
;   #define SCHED __builtin_amdgcn_sched_barrier(0)
; template <bool TWO, class MID> ...
;     ...
;     WAIT_V(6); BAR; MMA(1,1,At,B1); BAR;
;     LDB(B0,1,0); SCHED; LDA(At,1,0); STAGE_A(SA(0,1),1,t+2);
;     WAIT_L(8); BAR; WAIT_L(0); MMA(0,0,At,B0); BAR; SCHED;
;     LDB(B1,1,1); STAGE_B(SB(1,0),0,t+3);
;     BAR; WAIT_L(0); MMA(0,1,At,B1); BAR;
;     LDA(At,1,1); STAGE_A(SA(1,0),0,t+3);
;     BAR; WAIT_L(0); MMA(1,0,At,B0); BAR; SCHED;
	v_mfma_f32_16x16x32_bf16 v[30:33], v[216:219], v[182:185], v[30:33]
	v_mfma_f32_16x16x32_bf16 v[26:29], v[224:227], v[182:185], v[26:29]
	v_mfma_f32_16x16x32_bf16 v[22:25], v[216:219], v[190:193], v[22:25]
	v_mfma_f32_16x16x32_bf16 v[18:21], v[224:227], v[190:193], v[18:21]
	v_mfma_f32_16x16x32_bf16 v[14:17], v[216:219], v[200:203], v[14:17]
	v_mfma_f32_16x16x32_bf16 v[10:13], v[224:227], v[200:203], v[10:13]
	v_mfma_f32_16x16x32_bf16 v[6:9], v[216:219], v[208:211], v[6:9]
	v_mfma_f32_16x16x32_bf16 v[2:5], v[224:227], v[208:211], v[2:5]
	v_mfma_f32_16x16x32_bf16 v[30:33], v[220:223], v[186:189], v[30:33]
	v_mfma_f32_16x16x32_bf16 v[26:29], v[228:231], v[186:189], v[26:29]
	v_mfma_f32_16x16x32_bf16 v[22:25], v[220:223], v[196:199], v[22:25]
	v_mfma_f32_16x16x32_bf16 v[18:21], v[228:231], v[196:199], v[18:21]
	v_mfma_f32_16x16x32_bf16 v[14:17], v[220:223], v[204:207], v[14:17]
	v_mfma_f32_16x16x32_bf16 v[10:13], v[228:231], v[204:207], v[10:13]
	v_mfma_f32_16x16x32_bf16 v[6:9], v[220:223], v[212:215], v[6:9]
	v_mfma_f32_16x16x32_bf16 v[2:5], v[228:231], v[212:215], v[2:5]
	s_barrier
	s_setprio 0
	ds_read_b128 v[166:169], v145
	ds_read_b128 v[170:173], v145 offset:1024
	ds_read_b128 v[174:177], v145 offset:2048
	ds_read_b128 v[178:181], v145 offset:3072
	ds_read_b128 v[182:185], v141 offset:32768
	ds_read_b128 v[186:189], v141 offset:33792
	ds_read_b128 v[190:193], v139 offset:32768
	ds_read_b128 v[196:199], v139 offset:33792
	ds_read_b128 v[200:203], v137 offset:32768
	ds_read_b128 v[204:207], v137 offset:33792
	ds_read_b128 v[208:211], v135 offset:32768
	ds_read_b128 v[212:215], v135 offset:33792
	s_add_u32 s28, s19, 0x36080100
	s_addc_u32 s29, s24, 0
	s_add_u32 m0, s98, 0x4000
	global_load_lds_dwordx4 v132, s[28:29]
	s_add_u32 m0, s98, 0x6000
	global_load_lds_dwordx4 v130, s[28:29]
	s_waitcnt lgkmcnt(8)
	s_setprio 1
	s_barrier
	s_waitcnt lgkmcnt(0)
	v_mfma_f32_16x16x32_bf16 v[126:129], v[166:169], v[182:185], v[126:129]
	v_mfma_f32_16x16x32_bf16 v[122:125], v[174:177], v[182:185], v[122:125]
	v_mfma_f32_16x16x32_bf16 v[118:121], v[166:169], v[190:193], v[118:121]
	v_mfma_f32_16x16x32_bf16 v[114:117], v[174:177], v[190:193], v[114:117]
	v_mfma_f32_16x16x32_bf16 v[110:113], v[166:169], v[200:203], v[110:113]
	v_mfma_f32_16x16x32_bf16 v[106:109], v[174:177], v[200:203], v[106:109]
	v_mfma_f32_16x16x32_bf16 v[102:105], v[166:169], v[208:211], v[102:105]
	v_mfma_f32_16x16x32_bf16 v[98:101], v[174:177], v[208:211], v[98:101]
	v_mfma_f32_16x16x32_bf16 v[126:129], v[170:173], v[186:189], v[126:129]
	v_mfma_f32_16x16x32_bf16 v[122:125], v[178:181], v[186:189], v[122:125]
	v_mfma_f32_16x16x32_bf16 v[118:121], v[170:173], v[196:199], v[118:121]
	v_mfma_f32_16x16x32_bf16 v[114:117], v[178:181], v[196:199], v[114:117]
	v_mfma_f32_16x16x32_bf16 v[110:113], v[170:173], v[204:207], v[110:113]
	v_mfma_f32_16x16x32_bf16 v[106:109], v[178:181], v[204:207], v[106:109]
	v_mfma_f32_16x16x32_bf16 v[102:105], v[170:173], v[212:215], v[102:105]
	v_mfma_f32_16x16x32_bf16 v[98:101], v[178:181], v[212:215], v[98:101]
	s_barrier
	s_setprio 0
	ds_read_b128 v[216:219], v143
	ds_read_b128 v[220:223], v143 offset:1024
	ds_read_b128 v[224:227], v143 offset:2048
	ds_read_b128 v[228:231], v143 offset:3072
	s_add_u32 s28, s25, 0x3400180
	s_addc_u32 s29, s26, 0
	s_add_u32 m0, s98, 0x18000
	global_load_lds_dwordx4 v132, s[28:29]
	s_add_u32 m0, s98, 0x1a000
	global_load_lds_dwordx4 v130, s[28:29]
	s_setprio 1
	s_barrier
	s_waitcnt lgkmcnt(0)
	v_mfma_f32_16x16x32_bf16 v[94:97], v[216:219], v[182:185], v[94:97]
	v_mfma_f32_16x16x32_bf16 v[90:93], v[224:227], v[182:185], v[90:93]
	v_mfma_f32_16x16x32_bf16 v[86:89], v[216:219], v[190:193], v[86:89]
	v_mfma_f32_16x16x32_bf16 v[82:85], v[224:227], v[190:193], v[82:85]
	v_mfma_f32_16x16x32_bf16 v[78:81], v[216:219], v[200:203], v[78:81]
	v_mfma_f32_16x16x32_bf16 v[74:77], v[224:227], v[200:203], v[74:77]
	v_mfma_f32_16x16x32_bf16 v[70:73], v[216:219], v[208:211], v[70:73]
	v_mfma_f32_16x16x32_bf16 v[66:69], v[224:227], v[208:211], v[66:69]
	v_mfma_f32_16x16x32_bf16 v[94:97], v[220:223], v[186:189], v[94:97]
	v_mfma_f32_16x16x32_bf16 v[90:93], v[228:231], v[186:189], v[90:93]
	v_mfma_f32_16x16x32_bf16 v[86:89], v[220:223], v[196:199], v[86:89]
	v_mfma_f32_16x16x32_bf16 v[82:85], v[228:231], v[196:199], v[82:85]
	v_mfma_f32_16x16x32_bf16 v[78:81], v[220:223], v[204:207], v[78:81]
	v_mfma_f32_16x16x32_bf16 v[74:77], v[228:231], v[204:207], v[74:77]
	v_mfma_f32_16x16x32_bf16 v[70:73], v[220:223], v[212:215], v[70:73]
	v_mfma_f32_16x16x32_bf16 v[66:69], v[228:231], v[212:215], v[66:69]
	s_barrier
	s_setprio 0
	ds_read_b128 v[182:185], v141 offset:49152
	ds_read_b128 v[186:189], v141 offset:50176
	ds_read_b128 v[190:193], v139 offset:49152
	ds_read_b128 v[196:199], v139 offset:50176
	ds_read_b128 v[200:203], v137 offset:49152
	ds_read_b128 v[204:207], v137 offset:50176
	ds_read_b128 v[208:211], v135 offset:49152
	ds_read_b128 v[212:215], v135 offset:50176
	s_add_u32 s28, s19, 0x36000180
	s_addc_u32 s29, s24, 0
	s_add_u32 m0, s98, 0x8000
	global_load_lds_dwordx4 v132, s[28:29]
	s_add_u32 m0, s98, 0xa000
	global_load_lds_dwordx4 v130, s[28:29]
	s_setprio 1
	s_barrier
;   #define LDA(dst,b,h) for(int m=0;m<4;++m)for(int k=0;k<2;++k) \
;     dst[m][k]=*reinterpret_cast<const bf16x8*>((char*)SA(b,h)+lds_byte(wr*64+m*16+fr,k*32+fq*8))
;   #define LDB(dst,b,h) for(int n=0;n<2;++n)for(int k=0;k<2;++k) \
;     dst[n][k]=*reinterpret_cast<const bf16x8*>((char*)SB(b,h)+lds_byte(wc*32+n*16+fr,k*32+fq*8))
;   #define MMA(ai,bj,At,Bt_) do{__builtin_amdgcn_s_setprio(1); \
;     for(int m=0;m<4;++m)for(int n=0;n<2;++n)for(int k=0;k<2;++k) \
;       acc[ai][bj][m][n]=__builtin_amdgcn_mfma_f32_16x16x32_bf16(Bt_[n][k],At[m][k],acc[ai][bj][m][n],0,0,0); \
;     __builtin_amdgcn_s_setprio(0);}while(0)
;   #define WAIT_V(n) asm volatile("s_waitcnt vmcnt(" #n ")":::"memory")
;   #define WAIT_L(n) asm volatile("s_waitcnt lgkmcnt(" #n ")":::"memory")
;   #define BAR __builtin_amdgcn_s_barrier()
;   #define SCHED __builtin_amdgcn_sched_barrier(0)
; template <bool TWO, class MID> ...
;     ...
;     BAR; WAIT_L(0); MMA(1,0,At,B0); BAR; SCHED;
;     STAGE_B(SB(1,1),1,t+3);
;     WAIT_V(6); BAR; MMA(1,1,At,B1); BAR;
;   }
;   { LDB(B0,0,0); LDA(At,0,0); STAGE_A(SA(1,1),1,nt-1);
;     BAR; WAIT_L(0); MMA(0,0,At,B0); BAR;
;     LDB(B1,0,1); BAR; WAIT_L(0); MMA(0,1,At,B1); BAR;
	s_waitcnt lgkmcnt(0)
	v_mfma_f32_16x16x32_bf16 v[62:65], v[166:169], v[182:185], v[62:65]
	v_mfma_f32_16x16x32_bf16 v[58:61], v[174:177], v[182:185], v[58:61]
	v_mfma_f32_16x16x32_bf16 v[54:57], v[166:169], v[190:193], v[54:57]
	v_mfma_f32_16x16x32_bf16 v[50:53], v[174:177], v[190:193], v[50:53]
	v_mfma_f32_16x16x32_bf16 v[46:49], v[166:169], v[200:203], v[46:49]
	v_mfma_f32_16x16x32_bf16 v[42:45], v[174:177], v[200:203], v[42:45]
	v_mfma_f32_16x16x32_bf16 v[38:41], v[166:169], v[208:211], v[38:41]
	v_mfma_f32_16x16x32_bf16 v[34:37], v[174:177], v[208:211], v[34:37]
	v_mfma_f32_16x16x32_bf16 v[62:65], v[170:173], v[186:189], v[62:65]
	v_mfma_f32_16x16x32_bf16 v[58:61], v[178:181], v[186:189], v[58:61]
	v_mfma_f32_16x16x32_bf16 v[54:57], v[170:173], v[196:199], v[54:57]
	v_mfma_f32_16x16x32_bf16 v[50:53], v[178:181], v[196:199], v[50:53]
	v_mfma_f32_16x16x32_bf16 v[46:49], v[170:173], v[204:207], v[46:49]
	v_mfma_f32_16x16x32_bf16 v[42:45], v[178:181], v[204:207], v[42:45]
	v_mfma_f32_16x16x32_bf16 v[38:41], v[170:173], v[212:215], v[38:41]
	v_mfma_f32_16x16x32_bf16 v[34:37], v[178:181], v[212:215], v[34:37]
	s_barrier
	s_setprio 0
	s_add_u32 s24, s25, 0x3480180
	s_addc_u32 s25, s26, 0
	s_add_u32 m0, s98, 0x1c000
	global_load_lds_dwordx4 v132, s[24:25]
	s_add_u32 m0, s98, 0x1e000
	global_load_lds_dwordx4 v130, s[24:25]
	s_waitcnt vmcnt(6)
	s_setprio 1
	s_barrier
	v_mfma_f32_16x16x32_bf16 v[30:33], v[216:219], v[182:185], v[30:33]
	v_mfma_f32_16x16x32_bf16 v[26:29], v[224:227], v[182:185], v[26:29]
	v_mfma_f32_16x16x32_bf16 v[22:25], v[216:219], v[190:193], v[22:25]
	v_mfma_f32_16x16x32_bf16 v[18:21], v[224:227], v[190:193], v[18:21]
	v_mfma_f32_16x16x32_bf16 v[14:17], v[216:219], v[200:203], v[14:17]
	v_mfma_f32_16x16x32_bf16 v[10:13], v[224:227], v[200:203], v[10:13]
	v_mfma_f32_16x16x32_bf16 v[6:9], v[216:219], v[208:211], v[6:9]
	v_mfma_f32_16x16x32_bf16 v[2:5], v[224:227], v[208:211], v[2:5]
	v_mfma_f32_16x16x32_bf16 v[30:33], v[220:223], v[186:189], v[30:33]
	v_mfma_f32_16x16x32_bf16 v[26:29], v[228:231], v[186:189], v[26:29]
	v_mfma_f32_16x16x32_bf16 v[22:25], v[220:223], v[196:199], v[22:25]
	v_mfma_f32_16x16x32_bf16 v[18:21], v[228:231], v[196:199], v[18:21]
	v_mfma_f32_16x16x32_bf16 v[14:17], v[220:223], v[204:207], v[14:17]
	v_mfma_f32_16x16x32_bf16 v[10:13], v[228:231], v[204:207], v[10:13]
	v_mfma_f32_16x16x32_bf16 v[6:9], v[220:223], v[212:215], v[6:9]
	v_mfma_f32_16x16x32_bf16 v[2:5], v[228:231], v[212:215], v[2:5]
	s_setprio 0
	s_add_i32 s18, s18, 2
	s_add_u32 s4, s4, 0x100
	s_addc_u32 s5, s5, 0
	s_cmp_lt_u32 s18, 28
	s_barrier
	s_cbranch_scc1 .LBB0_489
	ds_read_b128 v[152:155], v149
	ds_read_b128 v[156:159], v149 offset:1024
	ds_read_b128 v[160:163], v149 offset:2048
	ds_read_b128 v[164:167], v149 offset:3072
	ds_read_b128 v[168:171], v141
	ds_read_b128 v[172:175], v141 offset:1024
	ds_read_b128 v[176:179], v139
	ds_read_b128 v[180:183], v139 offset:1024
	ds_read_b128 v[184:187], v137
	ds_read_b128 v[188:191], v137 offset:1024
	ds_read_b128 v[196:199], v135
	ds_read_b128 v[200:203], v135 offset:1024
	s_add_u32 s4, s12, 0x80f80
	s_addc_u32 s5, s13, 0
	v_lshl_add_u64 v[132:133], s[4:5], 0, v[132:133]
	v_readfirstlane_b32 s12, v148
	s_mov_b32 m0, s12
	global_load_lds_dwordx4 v[132:133], off
	v_lshl_add_u64 v[130:131], s[4:5], 0, v[130:131]
	v_readfirstlane_b32 s4, v150
	s_mov_b32 m0, s4
	global_load_lds_dwordx4 v[130:131], off
	s_setprio 1
	s_barrier
	s_waitcnt lgkmcnt(0)
	v_mfma_f32_16x16x32_bf16 v[126:129], v[152:155], v[168:171], v[126:129]
	v_mfma_f32_16x16x32_bf16 v[122:125], v[160:163], v[168:171], v[122:125]
	v_mfma_f32_16x16x32_bf16 v[118:121], v[152:155], v[176:179], v[118:121]
	v_mfma_f32_16x16x32_bf16 v[114:117], v[160:163], v[176:179], v[114:117]
	v_mfma_f32_16x16x32_bf16 v[102:105], v[152:155], v[196:199], v[102:105]
	v_mfma_f32_16x16x32_bf16 v[98:101], v[160:163], v[196:199], v[98:101]
	v_mfma_f32_16x16x32_bf16 v[126:129], v[156:159], v[172:175], v[126:129]
	v_mfma_f32_16x16x32_bf16 v[122:125], v[164:167], v[172:175], v[122:125]
	v_mfma_f32_16x16x32_bf16 v[118:121], v[156:159], v[180:183], v[118:121]
	v_mfma_f32_16x16x32_bf16 v[114:117], v[164:167], v[180:183], v[114:117]
	v_mfma_f32_16x16x32_bf16 v[110:113], v[152:155], v[184:187], v[110:113]
	v_mfma_f32_16x16x32_bf16 v[106:109], v[160:163], v[184:187], v[106:109]
	v_mfma_f32_16x16x32_bf16 v[102:105], v[156:159], v[200:203], v[102:105]
	v_mfma_f32_16x16x32_bf16 v[98:101], v[164:167], v[200:203], v[98:101]
	v_mfma_f32_16x16x32_bf16 v[130:133], v[156:159], v[188:191], v[110:113]
	v_mfma_f32_16x16x32_bf16 v[148:151], v[164:167], v[188:191], v[106:109]
	s_barrier
	s_setprio 0
	s_nop 0
	ds_read_b128 v[106:109], v147
	ds_read_b128 v[110:113], v147 offset:1024
	ds_read_b128 v[204:207], v147 offset:2048
	ds_read_b128 v[208:211], v147 offset:3072
	s_setprio 1
	s_barrier
	s_waitcnt lgkmcnt(0)
	v_mfma_f32_16x16x32_bf16 v[86:89], v[106:109], v[176:179], v[86:89]
	v_mfma_f32_16x16x32_bf16 v[82:85], v[204:207], v[176:179], v[82:85]
	v_mfma_f32_16x16x32_bf16 v[70:73], v[106:109], v[196:199], v[70:73]
	v_mfma_f32_16x16x32_bf16 v[66:69], v[204:207], v[196:199], v[66:69]
	v_mfma_f32_16x16x32_bf16 v[94:97], v[106:109], v[168:171], v[94:97]
	v_mfma_f32_16x16x32_bf16 v[90:93], v[204:207], v[168:171], v[90:93]
	v_mfma_f32_16x16x32_bf16 v[86:89], v[110:113], v[180:183], v[86:89]
	v_mfma_f32_16x16x32_bf16 v[82:85], v[208:211], v[180:183], v[82:85]
	v_mfma_f32_16x16x32_bf16 v[78:81], v[106:109], v[184:187], v[78:81]
	v_mfma_f32_16x16x32_bf16 v[74:77], v[204:207], v[184:187], v[74:77]
	v_mfma_f32_16x16x32_bf16 v[70:73], v[110:113], v[200:203], v[70:73]
	v_mfma_f32_16x16x32_bf16 v[66:69], v[208:211], v[200:203], v[66:69]
	v_mfma_f32_16x16x32_bf16 v[212:215], v[110:113], v[172:175], v[94:97]
	v_mfma_f32_16x16x32_bf16 v[168:171], v[208:211], v[172:175], v[90:93]
	v_mfma_f32_16x16x32_bf16 v[172:175], v[110:113], v[188:191], v[78:81]
	v_mfma_f32_16x16x32_bf16 v[176:179], v[208:211], v[188:191], v[74:77]
	s_barrier
;   #define LDA(dst,b,h) for(int m=0;m<4;++m)for(int k=0;k<2;++k) \
;     dst[m][k]=*reinterpret_cast<const bf16x8*>((char*)SA(b,h)+lds_byte(wr*64+m*16+fr,k*32+fq*8))
;   #define LDB(dst,b,h) for(int n=0;n<2;++n)for(int k=0;k<2;++k) \
;     dst[n][k]=*reinterpret_cast<const bf16x8*>((char*)SB(b,h)+lds_byte(wc*32+n*16+fr,k*32+fq*8))
;   #define MMA(ai,bj,At,Bt_) do{__builtin_amdgcn_s_setprio(1); \
;     for(int m=0;m<4;++m)for(int n=0;n<2;++n)for(int k=0;k<2;++k) \
;       acc[ai][bj][m][n]=__builtin_amdgcn_mfma_f32_16x16x32_bf16(Bt_[n][k],At[m][k],acc[ai][bj][m][n],0,0,0); \
;     __builtin_amdgcn_s_setprio(0);}while(0)
;   #define WAIT_V(n) asm volatile("s_waitcnt vmcnt(" #n ")":::"memory")
;   #define WAIT_L(n) asm volatile("s_waitcnt lgkmcnt(" #n ")":::"memory")
;   #define BAR __builtin_amdgcn_s_barrier()
; template <bool TWO, class MID> ...
;     ...
;     LDA(At,0,1); WAIT_V(4); BAR; WAIT_L(0); MMA(1,0,At,B0); MMA(1,1,At,B1); BAR; }
;   { LDB(B0,1,0); LDA(At,1,0); WAIT_V(2); BAR; WAIT_L(0); MMA(0,0,At,B0); BAR;
	s_setprio 0
	s_nop 0
	ds_read_b128 v[74:77], v141 offset:16384
	ds_read_b128 v[78:81], v141 offset:17408
	ds_read_b128 v[90:93], v139 offset:16384
	ds_read_b128 v[94:97], v139 offset:17408
	ds_read_b128 v[180:183], v137 offset:16384
	ds_read_b128 v[184:187], v137 offset:17408
	ds_read_b128 v[188:191], v135 offset:16384
	ds_read_b128 v[196:199], v135 offset:17408
	s_waitcnt vmcnt(4)
	s_setprio 1
	s_barrier
	s_waitcnt lgkmcnt(0)
	v_mfma_f32_16x16x32_bf16 v[62:65], v[152:155], v[74:77], v[62:65]
	v_mfma_f32_16x16x32_bf16 v[58:61], v[160:163], v[74:77], v[58:61]
	v_mfma_f32_16x16x32_bf16 v[54:57], v[152:155], v[90:93], v[54:57]
	v_mfma_f32_16x16x32_bf16 v[50:53], v[160:163], v[90:93], v[50:53]
	v_mfma_f32_16x16x32_bf16 v[38:41], v[152:155], v[188:191], v[38:41]
	v_mfma_f32_16x16x32_bf16 v[34:37], v[160:163], v[188:191], v[34:37]
	v_mfma_f32_16x16x32_bf16 v[62:65], v[156:159], v[78:81], v[62:65]
	v_mfma_f32_16x16x32_bf16 v[58:61], v[164:167], v[78:81], v[58:61]
	v_mfma_f32_16x16x32_bf16 v[54:57], v[156:159], v[94:97], v[54:57]
	v_mfma_f32_16x16x32_bf16 v[50:53], v[164:167], v[94:97], v[50:53]
	v_mfma_f32_16x16x32_bf16 v[46:49], v[152:155], v[180:183], v[46:49]
	v_mfma_f32_16x16x32_bf16 v[42:45], v[160:163], v[180:183], v[42:45]
	v_mfma_f32_16x16x32_bf16 v[38:41], v[156:159], v[196:199], v[38:41]
	v_mfma_f32_16x16x32_bf16 v[34:37], v[164:167], v[196:199], v[34:37]
	v_mfma_f32_16x16x32_bf16 v[200:203], v[156:159], v[184:187], v[46:49]
	v_mfma_f32_16x16x32_bf16 v[216:219], v[164:167], v[184:187], v[42:45]
	s_setprio 0
	s_setprio 1
	v_mfma_f32_16x16x32_bf16 v[22:25], v[106:109], v[90:93], v[22:25]
	v_mfma_f32_16x16x32_bf16 v[18:21], v[204:207], v[90:93], v[18:21]
	v_mfma_f32_16x16x32_bf16 v[6:9], v[106:109], v[188:191], v[6:9]
	v_mfma_f32_16x16x32_bf16 v[2:5], v[204:207], v[188:191], v[2:5]
	v_mfma_f32_16x16x32_bf16 v[30:33], v[106:109], v[74:77], v[30:33]
	v_mfma_f32_16x16x32_bf16 v[26:29], v[204:207], v[74:77], v[26:29]
	v_mfma_f32_16x16x32_bf16 v[22:25], v[110:113], v[94:97], v[22:25]
	v_mfma_f32_16x16x32_bf16 v[18:21], v[208:211], v[94:97], v[18:21]
	v_mfma_f32_16x16x32_bf16 v[14:17], v[106:109], v[180:183], v[14:17]
	v_mfma_f32_16x16x32_bf16 v[10:13], v[204:207], v[180:183], v[10:13]
	v_mfma_f32_16x16x32_bf16 v[6:9], v[110:113], v[196:199], v[6:9]
	v_mfma_f32_16x16x32_bf16 v[2:5], v[208:211], v[196:199], v[2:5]
	v_mfma_f32_16x16x32_bf16 v[152:155], v[110:113], v[78:81], v[30:33]
	v_mfma_f32_16x16x32_bf16 v[156:159], v[208:211], v[78:81], v[26:29]
	v_mfma_f32_16x16x32_bf16 v[160:163], v[110:113], v[184:187], v[14:17]
	v_mfma_f32_16x16x32_bf16 v[164:167], v[208:211], v[184:187], v[10:13]
	s_barrier
	s_setprio 0
	s_nop 0
	ds_read_b128 v[10:13], v145
	ds_read_b128 v[14:17], v145 offset:1024
	ds_read_b128 v[180:183], v145 offset:2048
	ds_read_b128 v[144:147], v145 offset:3072
	ds_read_b128 v[26:29], v141 offset:32768
	ds_read_b128 v[30:33], v141 offset:33792
	ds_read_b128 v[42:45], v139 offset:32768
	ds_read_b128 v[46:49], v139 offset:33792
	ds_read_b128 v[184:187], v137 offset:32768
	ds_read_b128 v[188:191], v137 offset:33792
	ds_read_b128 v[196:199], v135 offset:32768
	ds_read_b128 v[204:207], v135 offset:33792
	s_waitcnt vmcnt(2)
	s_setprio 1
	s_barrier
	s_waitcnt lgkmcnt(0)
	v_mfma_f32_16x16x32_bf16 v[74:77], v[10:13], v[26:29], v[126:129]
	v_mfma_f32_16x16x32_bf16 v[126:129], v[14:17], v[30:33], v[74:77]
	v_mfma_f32_16x16x32_bf16 v[74:77], v[180:183], v[26:29], v[122:125]
	v_mfma_f32_16x16x32_bf16 v[122:125], v[144:147], v[30:33], v[74:77]
	v_mfma_f32_16x16x32_bf16 v[74:77], v[10:13], v[42:45], v[118:121]
	v_mfma_f32_16x16x32_bf16 v[110:113], v[14:17], v[46:49], v[74:77]
	v_mfma_f32_16x16x32_bf16 v[74:77], v[180:183], v[42:45], v[114:117]
	v_mfma_f32_16x16x32_bf16 v[106:109], v[144:147], v[46:49], v[74:77]
	v_mfma_f32_16x16x32_bf16 v[74:77], v[10:13], v[184:187], v[130:133]
	v_mfma_f32_16x16x32_bf16 v[94:97], v[14:17], v[188:191], v[74:77]
	v_mfma_f32_16x16x32_bf16 v[74:77], v[180:183], v[184:187], v[148:151]
	v_mfma_f32_16x16x32_bf16 v[90:93], v[144:147], v[188:191], v[74:77]
	v_mfma_f32_16x16x32_bf16 v[74:77], v[10:13], v[196:199], v[102:105]
	v_mfma_f32_16x16x32_bf16 v[78:81], v[14:17], v[204:207], v[74:77]
	v_mfma_f32_16x16x32_bf16 v[74:77], v[180:183], v[196:199], v[98:101]
	v_mfma_f32_16x16x32_bf16 v[74:77], v[144:147], v[204:207], v[74:77]
	s_barrier
;   #define LDA(dst,b,h) for(int m=0;m<4;++m)for(int k=0;k<2;++k) \
;     dst[m][k]=*reinterpret_cast<const bf16x8*>((char*)SA(b,h)+lds_byte(wr*64+m*16+fr,k*32+fq*8))
;   #define LDB(dst,b,h) for(int n=0;n<2;++n)for(int k=0;k<2;++k) \
;     dst[n][k]=*reinterpret_cast<const bf16x8*>((char*)SB(b,h)+lds_byte(wc*32+n*16+fr,k*32+fq*8))
;   #define MMA(ai,bj,At,Bt_) do{__builtin_amdgcn_s_setprio(1); \
;     for(int m=0;m<4;++m)for(int n=0;n<2;++n)for(int k=0;k<2;++k) \
;       acc[ai][bj][m][n]=__builtin_amdgcn_mfma_f32_16x16x32_bf16(Bt_[n][k],At[m][k],acc[ai][bj][m][n],0,0,0); \
;     __builtin_amdgcn_s_setprio(0);}while(0)
;   #define WAIT_V(n) asm volatile("s_waitcnt vmcnt(" #n ")":::"memory")
;   #define WAIT_L(n) asm volatile("s_waitcnt lgkmcnt(" #n ")":::"memory")
;   #define BAR __builtin_amdgcn_s_barrier()
; template <bool TWO, class MID> ...
;     ...
;   { LDB(B0,1,0); LDA(At,1,0); WAIT_V(2); BAR; WAIT_L(0); MMA(0,0,At,B0); BAR;
;     LDB(B1,1,1); WAIT_V(0); BAR; WAIT_L(0); MMA(0,1,At,B1); BAR;
;     LDA(At,1,1); BAR; WAIT_L(0); MMA(1,0,At,B0); MMA(1,1,At,B1); BAR; }
;   if(wr==0)BAR;
	s_setprio 0
	ds_read_b128 v[130:133], v143
	ds_read_b128 v[148:151], v143 offset:1024
	ds_read_b128 v[208:211], v143 offset:2048
	ds_read_b128 v[220:223], v143 offset:3072
	s_waitcnt vmcnt(0)
	s_setprio 1
	s_barrier
	s_waitcnt lgkmcnt(0)
	v_mfma_f32_16x16x32_bf16 v[98:101], v[130:133], v[26:29], v[212:215]
	v_mfma_f32_16x16x32_bf16 v[26:29], v[208:211], v[26:29], v[168:171]
	v_mfma_f32_16x16x32_bf16 v[114:117], v[220:223], v[30:33], v[26:29]
	v_mfma_f32_16x16x32_bf16 v[26:29], v[130:133], v[42:45], v[86:89]
	v_mfma_f32_16x16x32_bf16 v[102:105], v[148:151], v[46:49], v[26:29]
	v_mfma_f32_16x16x32_bf16 v[26:29], v[208:211], v[42:45], v[82:85]
	v_mfma_f32_16x16x32_bf16 v[118:121], v[148:151], v[30:33], v[98:101]
	v_mfma_f32_16x16x32_bf16 v[98:101], v[220:223], v[46:49], v[26:29]
	v_mfma_f32_16x16x32_bf16 v[26:29], v[130:133], v[184:187], v[172:175]
	v_mfma_f32_16x16x32_bf16 v[86:89], v[148:151], v[188:191], v[26:29]
	v_mfma_f32_16x16x32_bf16 v[26:29], v[208:211], v[184:187], v[176:179]
	v_mfma_f32_16x16x32_bf16 v[82:85], v[220:223], v[188:191], v[26:29]
	v_mfma_f32_16x16x32_bf16 v[26:29], v[130:133], v[196:199], v[70:73]
	v_mfma_f32_16x16x32_bf16 v[70:73], v[148:151], v[204:207], v[26:29]
	v_mfma_f32_16x16x32_bf16 v[26:29], v[208:211], v[196:199], v[66:69]
	v_mfma_f32_16x16x32_bf16 v[66:69], v[220:223], v[204:207], v[26:29]
	s_barrier
	s_setprio 0
	ds_read_b128 v[168:171], v141 offset:49152
	ds_read_b128 v[140:143], v141 offset:50176
	ds_read_b128 v[172:175], v139 offset:49152
	ds_read_b128 v[176:179], v139 offset:50176
	ds_read_b128 v[184:187], v137 offset:49152
	ds_read_b128 v[136:139], v137 offset:50176
	ds_read_b128 v[188:191], v135 offset:49152
	ds_read_b128 v[196:199], v135 offset:50176
	s_setprio 1
	s_barrier
	s_waitcnt lgkmcnt(0)
	v_mfma_f32_16x16x32_bf16 v[26:29], v[10:13], v[168:171], v[62:65]
	v_mfma_f32_16x16x32_bf16 v[62:65], v[14:17], v[140:143], v[26:29]
	v_mfma_f32_16x16x32_bf16 v[26:29], v[180:183], v[168:171], v[58:61]
	v_mfma_f32_16x16x32_bf16 v[58:61], v[144:147], v[140:143], v[26:29]
	v_mfma_f32_16x16x32_bf16 v[26:29], v[10:13], v[172:175], v[54:57]
	v_mfma_f32_16x16x32_bf16 v[46:49], v[14:17], v[176:179], v[26:29]
	v_mfma_f32_16x16x32_bf16 v[26:29], v[180:183], v[172:175], v[50:53]
	v_mfma_f32_16x16x32_bf16 v[42:45], v[144:147], v[176:179], v[26:29]
	v_mfma_f32_16x16x32_bf16 v[26:29], v[10:13], v[184:187], v[200:203]
	v_mfma_f32_16x16x32_bf16 v[10:13], v[10:13], v[188:191], v[38:41]
	v_mfma_f32_16x16x32_bf16 v[30:33], v[14:17], v[136:139], v[26:29]
	v_mfma_f32_16x16x32_bf16 v[26:29], v[180:183], v[184:187], v[216:219]
	v_mfma_f32_16x16x32_bf16 v[14:17], v[14:17], v[196:199], v[10:13]
	v_mfma_f32_16x16x32_bf16 v[10:13], v[180:183], v[188:191], v[34:37]
	v_mfma_f32_16x16x32_bf16 v[26:29], v[144:147], v[136:139], v[26:29]
	v_mfma_f32_16x16x32_bf16 v[10:13], v[144:147], v[196:199], v[10:13]
	s_setprio 0
	s_setprio 1
	v_mfma_f32_16x16x32_bf16 v[34:37], v[130:133], v[168:171], v[152:155]
	v_mfma_f32_16x16x32_bf16 v[54:57], v[148:151], v[140:143], v[34:37]
	v_mfma_f32_16x16x32_bf16 v[34:37], v[208:211], v[168:171], v[156:159]
	v_mfma_f32_16x16x32_bf16 v[18:21], v[208:211], v[172:175], v[18:21]
	v_mfma_f32_16x16x32_bf16 v[50:53], v[220:223], v[140:143], v[34:37]
	v_mfma_f32_16x16x32_bf16 v[22:25], v[130:133], v[172:175], v[22:25]
	v_mfma_f32_16x16x32_bf16 v[34:37], v[220:223], v[176:179], v[18:21]
	v_mfma_f32_16x16x32_bf16 v[18:21], v[130:133], v[184:187], v[160:163]
	v_mfma_f32_16x16x32_bf16 v[38:41], v[148:151], v[176:179], v[22:25]
	v_mfma_f32_16x16x32_bf16 v[22:25], v[148:151], v[136:139], v[18:21]
	v_mfma_f32_16x16x32_bf16 v[18:21], v[208:211], v[184:187], v[164:167]
	v_mfma_f32_16x16x32_bf16 v[6:9], v[130:133], v[188:191], v[6:9]
	v_mfma_f32_16x16x32_bf16 v[2:5], v[208:211], v[188:191], v[2:5]
	v_mfma_f32_16x16x32_bf16 v[18:21], v[220:223], v[136:139], v[18:21]
	v_mfma_f32_16x16x32_bf16 v[6:9], v[148:151], v[196:199], v[6:9]
	v_mfma_f32_16x16x32_bf16 v[2:5], v[220:223], v[196:199], v[2:5]
	s_setprio 0
	v_cmp_gt_u32_e32 vcc, s30, v1
	s_barrier
	s_and_saveexec_b64 s[4:5], vcc
	s_cbranch_execz .LBB0_492
	s_barrier

;   #define LDA(dst,b,h) for(int m=0;m<4;++m)for(int k=0;k<2;++k) \
;     dst[m][k]=*reinterpret_cast<const bf16x8*>((char*)SA(b,h)+lds_byte(wr*64+m*16+fr,k*32+fq*8))
;   #define LDB(dst,b,h) for(int n=0;n<2;++n)for(int k=0;k<2;++k) \
;     dst[n][k]=*reinterpret_cast<const bf16x8*>((char*)SB(b,h)+lds_byte(wc*32+n*16+fr,k*32+fq*8))
;   #define MMA(ai,bj,At,Bt_) do{__builtin_amdgcn_s_setprio(1); \
;     for(int m=0;m<4;++m)for(int n=0;n<2;++n)for(int k=0;k<2;++k) \
;       acc[ai][bj][m][n]=__builtin_amdgcn_mfma_f32_16x16x32_bf16(Bt_[n][k],At[m][k],acc[ai][bj][m][n],0,0,0); \
;     __builtin_amdgcn_s_setprio(0);}while(0)
;   #define WAIT_V(n) asm volatile("s_waitcnt vmcnt(" #n ")":::"memory")
;   #define WAIT_L(n) asm volatile("s_waitcnt lgkmcnt(" #n ")":::"memory")
;   #define BAR __builtin_amdgcn_s_barrier()
;   #define SCHED __builtin_amdgcn_sched_barrier(0)
; template <bool TWO, class MID> ...
;     ...
;     LDB(B0,0,0); SCHED; LDA(At,0,0); STAGE_A(SA(1,1),1,t+1);
;     WAIT_L(8); BAR; WAIT_L(0); MMA(0,0,At,B0); BAR; SCHED;
;     LDB(B1,0,1); STAGE_B(SB(0,0),0,t+2);
;     BAR; WAIT_L(0); MMA(0,1,At,B1); BAR;
;     LDA(At,0,1); STAGE_A(SA(0,0),0,t+2);
;     BAR; WAIT_L(0); MMA(1,0,At,B0); BAR; SCHED;
;     STAGE_B(SB(0,1),1,t+2);
;     WAIT_V(6); BAR; MMA(1,1,At,B1); BAR;
.LBB0_562:
	ds_read_b128 v[166:169], v149
	ds_read_b128 v[170:173], v149 offset:1024
	ds_read_b128 v[174:177], v149 offset:2048
	ds_read_b128 v[178:181], v149 offset:3072
	ds_read_b128 v[182:185], v141
	ds_read_b128 v[186:189], v141 offset:1024
	ds_read_b128 v[190:193], v139
	ds_read_b128 v[196:199], v139 offset:1024
	ds_read_b128 v[200:203], v137
	ds_read_b128 v[204:207], v137 offset:1024
	ds_read_b128 v[208:211], v135
	ds_read_b128 v[212:215], v135 offset:1024
	s_add_u32 s23, s4, s12
	s_addc_u32 s24, s5, s13
	s_add_u32 s26, s23, 0x8080080
	s_addc_u32 s27, s24, 0
	s_add_u32 m0, s98, 0xc000
	global_load_lds_dwordx4 v132, s[26:27]
	s_add_u32 m0, s98, 0xe000
	global_load_lds_dwordx4 v130, s[26:27]
	s_waitcnt lgkmcnt(8)
	s_setprio 1
	s_barrier
	s_waitcnt lgkmcnt(0)
	v_mfma_f32_16x16x32_bf16 v[126:129], v[166:169], v[182:185], v[126:129]
	v_mfma_f32_16x16x32_bf16 v[122:125], v[174:177], v[182:185], v[122:125]
	v_mfma_f32_16x16x32_bf16 v[118:121], v[166:169], v[190:193], v[118:121]
	v_mfma_f32_16x16x32_bf16 v[114:117], v[174:177], v[190:193], v[114:117]
	v_mfma_f32_16x16x32_bf16 v[110:113], v[166:169], v[200:203], v[110:113]
	v_mfma_f32_16x16x32_bf16 v[106:109], v[174:177], v[200:203], v[106:109]
	v_mfma_f32_16x16x32_bf16 v[102:105], v[166:169], v[208:211], v[102:105]
	v_mfma_f32_16x16x32_bf16 v[98:101], v[174:177], v[208:211], v[98:101]
	v_mfma_f32_16x16x32_bf16 v[126:129], v[170:173], v[186:189], v[126:129]
	v_mfma_f32_16x16x32_bf16 v[122:125], v[178:181], v[186:189], v[122:125]
	v_mfma_f32_16x16x32_bf16 v[118:121], v[170:173], v[196:199], v[118:121]
	v_mfma_f32_16x16x32_bf16 v[114:117], v[178:181], v[196:199], v[114:117]
	v_mfma_f32_16x16x32_bf16 v[110:113], v[170:173], v[204:207], v[110:113]
	v_mfma_f32_16x16x32_bf16 v[106:109], v[178:181], v[204:207], v[106:109]
	v_mfma_f32_16x16x32_bf16 v[102:105], v[170:173], v[212:215], v[102:105]
	v_mfma_f32_16x16x32_bf16 v[98:101], v[178:181], v[212:215], v[98:101]
	s_barrier
	s_setprio 0
	s_add_u32 s25, s4, s14
	ds_read_b128 v[216:219], v147
	ds_read_b128 v[220:223], v147 offset:1024
	ds_read_b128 v[224:227], v147 offset:2048
	ds_read_b128 v[228:231], v147 offset:3072
	s_addc_u32 s26, s5, s15
	s_add_u32 s28, s25, 0x3c00100
	s_addc_u32 s29, s26, 0
	s_add_u32 m0, s98, 0x10000
	global_load_lds_dwordx4 v132, s[28:29]
	s_add_u32 m0, s98, 0x12000
	global_load_lds_dwordx4 v130, s[28:29]
	s_setprio 1
	s_barrier
	s_waitcnt lgkmcnt(0)
	v_mfma_f32_16x16x32_bf16 v[94:97], v[216:219], v[182:185], v[94:97]
	v_mfma_f32_16x16x32_bf16 v[90:93], v[224:227], v[182:185], v[90:93]
	v_mfma_f32_16x16x32_bf16 v[86:89], v[216:219], v[190:193], v[86:89]
	v_mfma_f32_16x16x32_bf16 v[82:85], v[224:227], v[190:193], v[82:85]
	v_mfma_f32_16x16x32_bf16 v[78:81], v[216:219], v[200:203], v[78:81]
	v_mfma_f32_16x16x32_bf16 v[74:77], v[224:227], v[200:203], v[74:77]
	v_mfma_f32_16x16x32_bf16 v[70:73], v[216:219], v[208:211], v[70:73]
	v_mfma_f32_16x16x32_bf16 v[66:69], v[224:227], v[208:211], v[66:69]
	v_mfma_f32_16x16x32_bf16 v[94:97], v[220:223], v[186:189], v[94:97]
	v_mfma_f32_16x16x32_bf16 v[90:93], v[228:231], v[186:189], v[90:93]
	v_mfma_f32_16x16x32_bf16 v[86:89], v[220:223], v[196:199], v[86:89]
	v_mfma_f32_16x16x32_bf16 v[82:85], v[228:231], v[196:199], v[82:85]
	v_mfma_f32_16x16x32_bf16 v[78:81], v[220:223], v[204:207], v[78:81]
	v_mfma_f32_16x16x32_bf16 v[74:77], v[228:231], v[204:207], v[74:77]
	v_mfma_f32_16x16x32_bf16 v[70:73], v[220:223], v[212:215], v[70:73]
	v_mfma_f32_16x16x32_bf16 v[66:69], v[228:231], v[212:215], v[66:69]
	s_barrier
	s_setprio 0
	ds_read_b128 v[182:185], v141 offset:16384
	ds_read_b128 v[186:189], v141 offset:17408
	ds_read_b128 v[190:193], v139 offset:16384
	ds_read_b128 v[196:199], v139 offset:17408
	ds_read_b128 v[200:203], v137 offset:16384
	ds_read_b128 v[204:207], v137 offset:17408
	ds_read_b128 v[208:211], v135 offset:16384
	ds_read_b128 v[212:215], v135 offset:17408
	s_add_u32 s28, s23, 0x8000100
	s_addc_u32 s29, s24, 0
	s_add_u32 m0, s98, 0x0
	global_load_lds_dwordx4 v132, s[28:29]
	s_add_u32 m0, s98, 0x2000
	global_load_lds_dwordx4 v130, s[28:29]
	s_setprio 1
	s_barrier
	s_waitcnt lgkmcnt(0)
	v_mfma_f32_16x16x32_bf16 v[62:65], v[166:169], v[182:185], v[62:65]
	v_mfma_f32_16x16x32_bf16 v[58:61], v[174:177], v[182:185], v[58:61]
	v_mfma_f32_16x16x32_bf16 v[54:57], v[166:169], v[190:193], v[54:57]
	v_mfma_f32_16x16x32_bf16 v[50:53], v[174:177], v[190:193], v[50:53]
	v_mfma_f32_16x16x32_bf16 v[46:49], v[166:169], v[200:203], v[46:49]
	v_mfma_f32_16x16x32_bf16 v[42:45], v[174:177], v[200:203], v[42:45]
	v_mfma_f32_16x16x32_bf16 v[38:41], v[166:169], v[208:211], v[38:41]
	v_mfma_f32_16x16x32_bf16 v[34:37], v[174:177], v[208:211], v[34:37]
	v_mfma_f32_16x16x32_bf16 v[62:65], v[170:173], v[186:189], v[62:65]
	v_mfma_f32_16x16x32_bf16 v[58:61], v[178:181], v[186:189], v[58:61]
	v_mfma_f32_16x16x32_bf16 v[54:57], v[170:173], v[196:199], v[54:57]
	v_mfma_f32_16x16x32_bf16 v[50:53], v[178:181], v[196:199], v[50:53]
	v_mfma_f32_16x16x32_bf16 v[46:49], v[170:173], v[204:207], v[46:49]
	v_mfma_f32_16x16x32_bf16 v[42:45], v[178:181], v[204:207], v[42:45]
	v_mfma_f32_16x16x32_bf16 v[38:41], v[170:173], v[212:215], v[38:41]
	v_mfma_f32_16x16x32_bf16 v[34:37], v[178:181], v[212:215], v[34:37]
	s_barrier
	s_setprio 0
	s_add_u32 s28, s25, 0x3c80100
	s_addc_u32 s29, s26, 0
	s_add_u32 m0, s98, 0x14000
	global_load_lds_dwordx4 v132, s[28:29]
	s_add_u32 m0, s98, 0x16000
	global_load_lds_dwordx4 v130, s[28:29]
	s_waitcnt vmcnt(6)
	s_setprio 1
	s_barrier
;   #define LDA(dst,b,h) for(int m=0;m<4;++m)for(int k=0;k<2;++k) \
;     dst[m][k]=*reinterpret_cast<const bf16x8*>((char*)SA(b,h)+lds_byte(wr*64+m*16+fr,k*32+fq*8))
;   #define LDB(dst,b,h) for(int n=0;n<2;++n)for(int k=0;k<2;++k) \
;     dst[n][k]=*reinterpret_cast<const bf16x8*>((char*)SB(b,h)+lds_byte(wc*32+n*16+fr,k*32+fq*8))
;   #define MMA(ai,bj,At,Bt_) do{__builtin_amdgcn_s_setprio(1); \
;     for(int m=0;m<4;++m)for(int n=0;n<2;++n)for(int k=0;k<2;++k) \
;       acc[ai][bj][m][n]=__builtin_amdgcn_mfma_f32_16x16x32_bf16(Bt_[n][k],At[m][k],acc[ai][bj][m][n],0,0,0); \
;     __builtin_amdgcn_s_setprio(0);}while(0)
;   #define WAIT_V(n) asm volatile("s_waitcnt vmcnt(" #n ")":::"memory")
;   #define WAIT_L(n) asm volatile("s_waitcnt lgkmcnt(" #n ")":::"memory")
;   #define BAR __builtin_amdgcn_s_barrier()
;   #define SCHED __builtin_amdgcn_sched_barrier(0)
; template <bool TWO, class MID> ...
;     ...
;     WAIT_V(6); BAR; MMA(1,1,At,B1); BAR;
;     LDB(B0,1,0); SCHED; LDA(At,1,0); STAGE_A(SA(0,1),1,t+2);
;     WAIT_L(8); BAR; WAIT_L(0); MMA(0,0,At,B0); BAR; SCHED;
;     LDB(B1,1,1); STAGE_B(SB(1,0),0,t+3);
;     BAR; WAIT_L(0); MMA(0,1,At,B1); BAR;
;     LDA(At,1,1); STAGE_A(SA(1,0),0,t+3);
;     BAR; WAIT_L(0); MMA(1,0,At,B0); BAR; SCHED;
	v_mfma_f32_16x16x32_bf16 v[30:33], v[216:219], v[182:185], v[30:33]
	v_mfma_f32_16x16x32_bf16 v[26:29], v[224:227], v[182:185], v[26:29]
	v_mfma_f32_16x16x32_bf16 v[22:25], v[216:219], v[190:193], v[22:25]
	v_mfma_f32_16x16x32_bf16 v[18:21], v[224:227], v[190:193], v[18:21]
	v_mfma_f32_16x16x32_bf16 v[14:17], v[216:219], v[200:203], v[14:17]
	v_mfma_f32_16x16x32_bf16 v[10:13], v[224:227], v[200:203], v[10:13]
	v_mfma_f32_16x16x32_bf16 v[6:9], v[216:219], v[208:211], v[6:9]
	v_mfma_f32_16x16x32_bf16 v[2:5], v[224:227], v[208:211], v[2:5]
	v_mfma_f32_16x16x32_bf16 v[30:33], v[220:223], v[186:189], v[30:33]
	v_mfma_f32_16x16x32_bf16 v[26:29], v[228:231], v[186:189], v[26:29]
	v_mfma_f32_16x16x32_bf16 v[22:25], v[220:223], v[196:199], v[22:25]
	v_mfma_f32_16x16x32_bf16 v[18:21], v[228:231], v[196:199], v[18:21]
	v_mfma_f32_16x16x32_bf16 v[14:17], v[220:223], v[204:207], v[14:17]
	v_mfma_f32_16x16x32_bf16 v[10:13], v[228:231], v[204:207], v[10:13]
	v_mfma_f32_16x16x32_bf16 v[6:9], v[220:223], v[212:215], v[6:9]
	v_mfma_f32_16x16x32_bf16 v[2:5], v[228:231], v[212:215], v[2:5]
	s_barrier
	s_setprio 0
	ds_read_b128 v[166:169], v145
	ds_read_b128 v[170:173], v145 offset:1024
	ds_read_b128 v[174:177], v145 offset:2048
	ds_read_b128 v[178:181], v145 offset:3072
	ds_read_b128 v[182:185], v141 offset:32768
	ds_read_b128 v[186:189], v141 offset:33792
	ds_read_b128 v[190:193], v139 offset:32768
	ds_read_b128 v[196:199], v139 offset:33792
	ds_read_b128 v[200:203], v137 offset:32768
	ds_read_b128 v[204:207], v137 offset:33792
	ds_read_b128 v[208:211], v135 offset:32768
	ds_read_b128 v[212:215], v135 offset:33792
	s_add_u32 s28, s23, 0x8080100
	s_addc_u32 s29, s24, 0
	s_add_u32 m0, s98, 0x4000
	global_load_lds_dwordx4 v132, s[28:29]
	s_add_u32 m0, s98, 0x6000
	global_load_lds_dwordx4 v130, s[28:29]
	s_waitcnt lgkmcnt(8)
	s_setprio 1
	s_barrier
	s_waitcnt lgkmcnt(0)
	v_mfma_f32_16x16x32_bf16 v[126:129], v[166:169], v[182:185], v[126:129]
	v_mfma_f32_16x16x32_bf16 v[122:125], v[174:177], v[182:185], v[122:125]
	v_mfma_f32_16x16x32_bf16 v[118:121], v[166:169], v[190:193], v[118:121]
	v_mfma_f32_16x16x32_bf16 v[114:117], v[174:177], v[190:193], v[114:117]
	v_mfma_f32_16x16x32_bf16 v[110:113], v[166:169], v[200:203], v[110:113]
	v_mfma_f32_16x16x32_bf16 v[106:109], v[174:177], v[200:203], v[106:109]
	v_mfma_f32_16x16x32_bf16 v[102:105], v[166:169], v[208:211], v[102:105]
	v_mfma_f32_16x16x32_bf16 v[98:101], v[174:177], v[208:211], v[98:101]
	v_mfma_f32_16x16x32_bf16 v[126:129], v[170:173], v[186:189], v[126:129]
	v_mfma_f32_16x16x32_bf16 v[122:125], v[178:181], v[186:189], v[122:125]
	v_mfma_f32_16x16x32_bf16 v[118:121], v[170:173], v[196:199], v[118:121]
	v_mfma_f32_16x16x32_bf16 v[114:117], v[178:181], v[196:199], v[114:117]
	v_mfma_f32_16x16x32_bf16 v[110:113], v[170:173], v[204:207], v[110:113]
	v_mfma_f32_16x16x32_bf16 v[106:109], v[178:181], v[204:207], v[106:109]
	v_mfma_f32_16x16x32_bf16 v[102:105], v[170:173], v[212:215], v[102:105]
	v_mfma_f32_16x16x32_bf16 v[98:101], v[178:181], v[212:215], v[98:101]
	s_barrier
	s_setprio 0
	ds_read_b128 v[216:219], v143
	ds_read_b128 v[220:223], v143 offset:1024
	ds_read_b128 v[224:227], v143 offset:2048
	ds_read_b128 v[228:231], v143 offset:3072
	s_add_u32 s28, s25, 0x3c00180
	s_addc_u32 s29, s26, 0
	s_add_u32 m0, s98, 0x18000
	global_load_lds_dwordx4 v132, s[28:29]
	s_add_u32 m0, s98, 0x1a000
	global_load_lds_dwordx4 v130, s[28:29]
	s_setprio 1
	s_barrier
	s_waitcnt lgkmcnt(0)
	v_mfma_f32_16x16x32_bf16 v[94:97], v[216:219], v[182:185], v[94:97]
	v_mfma_f32_16x16x32_bf16 v[90:93], v[224:227], v[182:185], v[90:93]
	v_mfma_f32_16x16x32_bf16 v[86:89], v[216:219], v[190:193], v[86:89]
	v_mfma_f32_16x16x32_bf16 v[82:85], v[224:227], v[190:193], v[82:85]
	v_mfma_f32_16x16x32_bf16 v[78:81], v[216:219], v[200:203], v[78:81]
	v_mfma_f32_16x16x32_bf16 v[74:77], v[224:227], v[200:203], v[74:77]
	v_mfma_f32_16x16x32_bf16 v[70:73], v[216:219], v[208:211], v[70:73]
	v_mfma_f32_16x16x32_bf16 v[66:69], v[224:227], v[208:211], v[66:69]
	v_mfma_f32_16x16x32_bf16 v[94:97], v[220:223], v[186:189], v[94:97]
	v_mfma_f32_16x16x32_bf16 v[90:93], v[228:231], v[186:189], v[90:93]
	v_mfma_f32_16x16x32_bf16 v[86:89], v[220:223], v[196:199], v[86:89]
	v_mfma_f32_16x16x32_bf16 v[82:85], v[228:231], v[196:199], v[82:85]
	v_mfma_f32_16x16x32_bf16 v[78:81], v[220:223], v[204:207], v[78:81]
	v_mfma_f32_16x16x32_bf16 v[74:77], v[228:231], v[204:207], v[74:77]
	v_mfma_f32_16x16x32_bf16 v[70:73], v[220:223], v[212:215], v[70:73]
	v_mfma_f32_16x16x32_bf16 v[66:69], v[228:231], v[212:215], v[66:69]
	s_barrier
	s_setprio 0
	ds_read_b128 v[182:185], v141 offset:49152
	ds_read_b128 v[186:189], v141 offset:50176
	ds_read_b128 v[190:193], v139 offset:49152
	ds_read_b128 v[196:199], v139 offset:50176
	ds_read_b128 v[200:203], v137 offset:49152
	ds_read_b128 v[204:207], v137 offset:50176
	ds_read_b128 v[208:211], v135 offset:49152
	ds_read_b128 v[212:215], v135 offset:50176
	s_add_u32 s28, s23, 0x8000180
	s_addc_u32 s29, s24, 0
	s_add_u32 m0, s98, 0x8000
	global_load_lds_dwordx4 v132, s[28:29]
	s_add_u32 m0, s98, 0xa000
	global_load_lds_dwordx4 v130, s[28:29]
	s_setprio 1
	s_barrier
;   #define LDA(dst,b,h) for(int m=0;m<4;++m)for(int k=0;k<2;++k) \
;     dst[m][k]=*reinterpret_cast<const bf16x8*>((char*)SA(b,h)+lds_byte(wr*64+m*16+fr,k*32+fq*8))
;   #define LDB(dst,b,h) for(int n=0;n<2;++n)for(int k=0;k<2;++k) \
;     dst[n][k]=*reinterpret_cast<const bf16x8*>((char*)SB(b,h)+lds_byte(wc*32+n*16+fr,k*32+fq*8))
;   #define MMA(ai,bj,At,Bt_) do{__builtin_amdgcn_s_setprio(1); \
;     for(int m=0;m<4;++m)for(int n=0;n<2;++n)for(int k=0;k<2;++k) \
;       acc[ai][bj][m][n]=__builtin_amdgcn_mfma_f32_16x16x32_bf16(Bt_[n][k],At[m][k],acc[ai][bj][m][n],0,0,0); \
;     __builtin_amdgcn_s_setprio(0);}while(0)
;   #define WAIT_V(n) asm volatile("s_waitcnt vmcnt(" #n ")":::"memory")
;   #define WAIT_L(n) asm volatile("s_waitcnt lgkmcnt(" #n ")":::"memory")
;   #define BAR __builtin_amdgcn_s_barrier()
;   #define SCHED __builtin_amdgcn_sched_barrier(0)
; template <bool TWO, class MID> ...
;     ...
;     BAR; WAIT_L(0); MMA(1,0,At,B0); BAR; SCHED;
;     STAGE_B(SB(1,1),1,t+3);
;     WAIT_V(6); BAR; MMA(1,1,At,B1); BAR;
;   }
;   { LDB(B0,0,0); LDA(At,0,0); STAGE_A(SA(1,1),1,nt-1);
;     BAR; WAIT_L(0); MMA(0,0,At,B0); BAR;
;     LDB(B1,0,1); BAR; WAIT_L(0); MMA(0,1,At,B1); BAR;
	s_waitcnt lgkmcnt(0)
	v_mfma_f32_16x16x32_bf16 v[62:65], v[166:169], v[182:185], v[62:65]
	v_mfma_f32_16x16x32_bf16 v[58:61], v[174:177], v[182:185], v[58:61]
	v_mfma_f32_16x16x32_bf16 v[54:57], v[166:169], v[190:193], v[54:57]
	v_mfma_f32_16x16x32_bf16 v[50:53], v[174:177], v[190:193], v[50:53]
	v_mfma_f32_16x16x32_bf16 v[46:49], v[166:169], v[200:203], v[46:49]
	v_mfma_f32_16x16x32_bf16 v[42:45], v[174:177], v[200:203], v[42:45]
	v_mfma_f32_16x16x32_bf16 v[38:41], v[166:169], v[208:211], v[38:41]
	v_mfma_f32_16x16x32_bf16 v[34:37], v[174:177], v[208:211], v[34:37]
	v_mfma_f32_16x16x32_bf16 v[62:65], v[170:173], v[186:189], v[62:65]
	v_mfma_f32_16x16x32_bf16 v[58:61], v[178:181], v[186:189], v[58:61]
	v_mfma_f32_16x16x32_bf16 v[54:57], v[170:173], v[196:199], v[54:57]
	v_mfma_f32_16x16x32_bf16 v[50:53], v[178:181], v[196:199], v[50:53]
	v_mfma_f32_16x16x32_bf16 v[46:49], v[170:173], v[204:207], v[46:49]
	v_mfma_f32_16x16x32_bf16 v[42:45], v[178:181], v[204:207], v[42:45]
	v_mfma_f32_16x16x32_bf16 v[38:41], v[170:173], v[212:215], v[38:41]
	v_mfma_f32_16x16x32_bf16 v[34:37], v[178:181], v[212:215], v[34:37]
	s_barrier
	s_setprio 0
	s_add_u32 s24, s25, 0x3c80180
	s_addc_u32 s25, s26, 0
	s_add_u32 m0, s98, 0x1c000
	global_load_lds_dwordx4 v132, s[24:25]
	s_add_u32 m0, s98, 0x1e000
	global_load_lds_dwordx4 v130, s[24:25]
	s_waitcnt vmcnt(6)
	s_setprio 1
	s_barrier
	v_mfma_f32_16x16x32_bf16 v[30:33], v[216:219], v[182:185], v[30:33]
	v_mfma_f32_16x16x32_bf16 v[26:29], v[224:227], v[182:185], v[26:29]
	v_mfma_f32_16x16x32_bf16 v[22:25], v[216:219], v[190:193], v[22:25]
	v_mfma_f32_16x16x32_bf16 v[18:21], v[224:227], v[190:193], v[18:21]
	v_mfma_f32_16x16x32_bf16 v[14:17], v[216:219], v[200:203], v[14:17]
	v_mfma_f32_16x16x32_bf16 v[10:13], v[224:227], v[200:203], v[10:13]
	v_mfma_f32_16x16x32_bf16 v[6:9], v[216:219], v[208:211], v[6:9]
	v_mfma_f32_16x16x32_bf16 v[2:5], v[224:227], v[208:211], v[2:5]
	v_mfma_f32_16x16x32_bf16 v[30:33], v[220:223], v[186:189], v[30:33]
	v_mfma_f32_16x16x32_bf16 v[26:29], v[228:231], v[186:189], v[26:29]
	v_mfma_f32_16x16x32_bf16 v[22:25], v[220:223], v[196:199], v[22:25]
	v_mfma_f32_16x16x32_bf16 v[18:21], v[228:231], v[196:199], v[18:21]
	v_mfma_f32_16x16x32_bf16 v[14:17], v[220:223], v[204:207], v[14:17]
	v_mfma_f32_16x16x32_bf16 v[10:13], v[228:231], v[204:207], v[10:13]
	v_mfma_f32_16x16x32_bf16 v[6:9], v[220:223], v[212:215], v[6:9]
	v_mfma_f32_16x16x32_bf16 v[2:5], v[228:231], v[212:215], v[2:5]
	s_setprio 0
	s_add_i32 s22, s22, 2
	s_add_u32 s4, s4, 0x100
	s_addc_u32 s5, s5, 0
	s_cmp_lt_u32 s22, 28
	s_barrier
	s_cbranch_scc1 .LBB0_562
	ds_read_b128 v[152:155], v149
	ds_read_b128 v[156:159], v149 offset:1024
	ds_read_b128 v[160:163], v149 offset:2048
	ds_read_b128 v[164:167], v149 offset:3072
	ds_read_b128 v[168:171], v141
	ds_read_b128 v[172:175], v141 offset:1024
	ds_read_b128 v[176:179], v139
	ds_read_b128 v[180:183], v139 offset:1024
	ds_read_b128 v[184:187], v137
	ds_read_b128 v[188:191], v137 offset:1024
	ds_read_b128 v[196:199], v135
	ds_read_b128 v[200:203], v135 offset:1024
	s_add_u32 s4, s19, 0x80f80
	s_addc_u32 s5, s21, 0
	v_lshl_add_u64 v[132:133], s[4:5], 0, v[132:133]
	v_readfirstlane_b32 s12, v148
	s_mov_b32 m0, s12
	global_load_lds_dwordx4 v[132:133], off
	v_lshl_add_u64 v[130:131], s[4:5], 0, v[130:131]
	v_readfirstlane_b32 s4, v150
	s_mov_b32 m0, s4
	global_load_lds_dwordx4 v[130:131], off
	s_setprio 1
	s_barrier
	s_waitcnt lgkmcnt(0)
	v_mfma_f32_16x16x32_bf16 v[126:129], v[152:155], v[168:171], v[126:129]
	v_mfma_f32_16x16x32_bf16 v[122:125], v[160:163], v[168:171], v[122:125]
	v_mfma_f32_16x16x32_bf16 v[114:117], v[160:163], v[176:179], v[114:117]
	v_mfma_f32_16x16x32_bf16 v[106:109], v[160:163], v[184:187], v[106:109]
	v_mfma_f32_16x16x32_bf16 v[98:101], v[160:163], v[196:199], v[98:101]
	v_mfma_f32_16x16x32_bf16 v[126:129], v[156:159], v[172:175], v[126:129]
	v_mfma_f32_16x16x32_bf16 v[122:125], v[164:167], v[172:175], v[122:125]
	v_mfma_f32_16x16x32_bf16 v[118:121], v[152:155], v[176:179], v[118:121]
	v_mfma_f32_16x16x32_bf16 v[114:117], v[164:167], v[180:183], v[114:117]
	v_mfma_f32_16x16x32_bf16 v[110:113], v[152:155], v[184:187], v[110:113]
	v_mfma_f32_16x16x32_bf16 v[106:109], v[164:167], v[188:191], v[106:109]
	v_mfma_f32_16x16x32_bf16 v[102:105], v[152:155], v[196:199], v[102:105]
	v_mfma_f32_16x16x32_bf16 v[98:101], v[164:167], v[200:203], v[98:101]
	v_mfma_f32_16x16x32_bf16 v[130:133], v[156:159], v[180:183], v[118:121]
	v_mfma_f32_16x16x32_bf16 v[148:151], v[156:159], v[188:191], v[110:113]
	v_mfma_f32_16x16x32_bf16 v[204:207], v[156:159], v[200:203], v[102:105]
	s_barrier
	s_setprio 0
	s_nop 0
	ds_read_b128 v[102:105], v147
	ds_read_b128 v[110:113], v147 offset:1024
	ds_read_b128 v[118:121], v147 offset:2048
	ds_read_b128 v[208:211], v147 offset:3072
	s_setprio 1
	s_barrier
	s_waitcnt lgkmcnt(0)
	v_mfma_f32_16x16x32_bf16 v[90:93], v[118:121], v[168:171], v[90:93]
	v_mfma_f32_16x16x32_bf16 v[82:85], v[118:121], v[176:179], v[82:85]
	v_mfma_f32_16x16x32_bf16 v[74:77], v[118:121], v[184:187], v[74:77]
	v_mfma_f32_16x16x32_bf16 v[66:69], v[118:121], v[196:199], v[66:69]
	v_mfma_f32_16x16x32_bf16 v[94:97], v[102:105], v[168:171], v[94:97]
	v_mfma_f32_16x16x32_bf16 v[90:93], v[208:211], v[172:175], v[90:93]
	v_mfma_f32_16x16x32_bf16 v[86:89], v[102:105], v[176:179], v[86:89]
	v_mfma_f32_16x16x32_bf16 v[82:85], v[208:211], v[180:183], v[82:85]
	v_mfma_f32_16x16x32_bf16 v[78:81], v[102:105], v[184:187], v[78:81]
	v_mfma_f32_16x16x32_bf16 v[74:77], v[208:211], v[188:191], v[74:77]
	v_mfma_f32_16x16x32_bf16 v[70:73], v[102:105], v[196:199], v[70:73]
	v_mfma_f32_16x16x32_bf16 v[66:69], v[208:211], v[200:203], v[66:69]
	v_mfma_f32_16x16x32_bf16 v[212:215], v[110:113], v[172:175], v[94:97]
	v_mfma_f32_16x16x32_bf16 v[168:171], v[110:113], v[180:183], v[86:89]
	v_mfma_f32_16x16x32_bf16 v[172:175], v[110:113], v[188:191], v[78:81]
	v_mfma_f32_16x16x32_bf16 v[176:179], v[110:113], v[200:203], v[70:73]
	s_barrier
;   #define LDA(dst,b,h) for(int m=0;m<4;++m)for(int k=0;k<2;++k) \
;     dst[m][k]=*reinterpret_cast<const bf16x8*>((char*)SA(b,h)+lds_byte(wr*64+m*16+fr,k*32+fq*8))
;   #define LDB(dst,b,h) for(int n=0;n<2;++n)for(int k=0;k<2;++k) \
;     dst[n][k]=*reinterpret_cast<const bf16x8*>((char*)SB(b,h)+lds_byte(wc*32+n*16+fr,k*32+fq*8))
;   #define MMA(ai,bj,At,Bt_) do{__builtin_amdgcn_s_setprio(1); \
;     for(int m=0;m<4;++m)for(int n=0;n<2;++n)for(int k=0;k<2;++k) \
;       acc[ai][bj][m][n]=__builtin_amdgcn_mfma_f32_16x16x32_bf16(Bt_[n][k],At[m][k],acc[ai][bj][m][n],0,0,0); \
;     __builtin_amdgcn_s_setprio(0);}while(0)
;   #define WAIT_V(n) asm volatile("s_waitcnt vmcnt(" #n ")":::"memory")
;   #define WAIT_L(n) asm volatile("s_waitcnt lgkmcnt(" #n ")":::"memory")
;   #define BAR __builtin_amdgcn_s_barrier()
; template <bool TWO, class MID> ...
;     ...
;     LDA(At,0,1); WAIT_V(4); BAR; WAIT_L(0); MMA(1,0,At,B0); MMA(1,1,At,B1); BAR; }
;   { LDB(B0,1,0); LDA(At,1,0); WAIT_V(2); BAR; WAIT_L(0); MMA(0,0,At,B0); BAR;
	s_setprio 0
	s_nop 0
	ds_read_b128 v[70:73], v141 offset:16384
	ds_read_b128 v[78:81], v141 offset:17408
	ds_read_b128 v[86:89], v139 offset:16384
	ds_read_b128 v[94:97], v139 offset:17408
	ds_read_b128 v[180:183], v137 offset:16384
	ds_read_b128 v[184:187], v137 offset:17408
	ds_read_b128 v[188:191], v135 offset:16384
	ds_read_b128 v[196:199], v135 offset:17408
	s_waitcnt vmcnt(4)
	s_setprio 1
	s_barrier
	s_waitcnt lgkmcnt(0)
	v_mfma_f32_16x16x32_bf16 v[62:65], v[152:155], v[70:73], v[62:65]
	v_mfma_f32_16x16x32_bf16 v[58:61], v[160:163], v[70:73], v[58:61]
	v_mfma_f32_16x16x32_bf16 v[54:57], v[152:155], v[86:89], v[54:57]
	v_mfma_f32_16x16x32_bf16 v[50:53], v[160:163], v[86:89], v[50:53]
	v_mfma_f32_16x16x32_bf16 v[38:41], v[152:155], v[188:191], v[38:41]
	v_mfma_f32_16x16x32_bf16 v[34:37], v[160:163], v[188:191], v[34:37]
	v_mfma_f32_16x16x32_bf16 v[62:65], v[156:159], v[78:81], v[62:65]
	v_mfma_f32_16x16x32_bf16 v[58:61], v[164:167], v[78:81], v[58:61]
	v_mfma_f32_16x16x32_bf16 v[54:57], v[156:159], v[94:97], v[54:57]
	v_mfma_f32_16x16x32_bf16 v[50:53], v[164:167], v[94:97], v[50:53]
	v_mfma_f32_16x16x32_bf16 v[46:49], v[152:155], v[180:183], v[46:49]
	v_mfma_f32_16x16x32_bf16 v[42:45], v[160:163], v[180:183], v[42:45]
	v_mfma_f32_16x16x32_bf16 v[38:41], v[156:159], v[196:199], v[38:41]
	v_mfma_f32_16x16x32_bf16 v[34:37], v[164:167], v[196:199], v[34:37]
	v_mfma_f32_16x16x32_bf16 v[200:203], v[156:159], v[184:187], v[46:49]
	v_mfma_f32_16x16x32_bf16 v[216:219], v[164:167], v[184:187], v[42:45]
	s_setprio 0
	s_setprio 1
	v_mfma_f32_16x16x32_bf16 v[22:25], v[102:105], v[86:89], v[22:25]
	v_mfma_f32_16x16x32_bf16 v[18:21], v[118:121], v[86:89], v[18:21]
	v_mfma_f32_16x16x32_bf16 v[6:9], v[102:105], v[188:191], v[6:9]
	v_mfma_f32_16x16x32_bf16 v[2:5], v[118:121], v[188:191], v[2:5]
	v_mfma_f32_16x16x32_bf16 v[30:33], v[102:105], v[70:73], v[30:33]
	v_mfma_f32_16x16x32_bf16 v[26:29], v[118:121], v[70:73], v[26:29]
	v_mfma_f32_16x16x32_bf16 v[22:25], v[110:113], v[94:97], v[22:25]
	v_mfma_f32_16x16x32_bf16 v[18:21], v[208:211], v[94:97], v[18:21]
	v_mfma_f32_16x16x32_bf16 v[14:17], v[102:105], v[180:183], v[14:17]
	v_mfma_f32_16x16x32_bf16 v[10:13], v[118:121], v[180:183], v[10:13]
	v_mfma_f32_16x16x32_bf16 v[6:9], v[110:113], v[196:199], v[6:9]
	v_mfma_f32_16x16x32_bf16 v[2:5], v[208:211], v[196:199], v[2:5]
	v_mfma_f32_16x16x32_bf16 v[152:155], v[110:113], v[78:81], v[30:33]
	v_mfma_f32_16x16x32_bf16 v[156:159], v[208:211], v[78:81], v[26:29]
	v_mfma_f32_16x16x32_bf16 v[160:163], v[110:113], v[184:187], v[14:17]
	v_mfma_f32_16x16x32_bf16 v[164:167], v[208:211], v[184:187], v[10:13]
	s_barrier
	s_setprio 0
	s_nop 0
	ds_read_b128 v[10:13], v145
	ds_read_b128 v[14:17], v145 offset:1024
	ds_read_b128 v[180:183], v145 offset:2048
	ds_read_b128 v[144:147], v145 offset:3072
	ds_read_b128 v[26:29], v141 offset:32768
	ds_read_b128 v[30:33], v141 offset:33792
	ds_read_b128 v[42:45], v139 offset:32768
	ds_read_b128 v[46:49], v139 offset:33792
	ds_read_b128 v[184:187], v137 offset:32768
	ds_read_b128 v[188:191], v137 offset:33792
	ds_read_b128 v[196:199], v135 offset:32768
	ds_read_b128 v[208:211], v135 offset:33792
	s_waitcnt vmcnt(2)
	s_setprio 1
	s_barrier
	s_waitcnt lgkmcnt(0)
	v_mfma_f32_16x16x32_bf16 v[70:73], v[10:13], v[26:29], v[126:129]
	v_mfma_f32_16x16x32_bf16 v[126:129], v[14:17], v[30:33], v[70:73]
	v_mfma_f32_16x16x32_bf16 v[70:73], v[180:183], v[26:29], v[122:125]
	v_mfma_f32_16x16x32_bf16 v[118:121], v[144:147], v[30:33], v[70:73]
	v_mfma_f32_16x16x32_bf16 v[70:73], v[10:13], v[42:45], v[130:133]
	v_mfma_f32_16x16x32_bf16 v[110:113], v[14:17], v[46:49], v[70:73]
	v_mfma_f32_16x16x32_bf16 v[70:73], v[180:183], v[42:45], v[114:117]
	v_mfma_f32_16x16x32_bf16 v[102:105], v[144:147], v[46:49], v[70:73]
	v_mfma_f32_16x16x32_bf16 v[70:73], v[10:13], v[184:187], v[148:151]
	v_mfma_f32_16x16x32_bf16 v[94:97], v[14:17], v[188:191], v[70:73]
	v_mfma_f32_16x16x32_bf16 v[70:73], v[180:183], v[184:187], v[106:109]
	v_mfma_f32_16x16x32_bf16 v[86:89], v[144:147], v[188:191], v[70:73]
	v_mfma_f32_16x16x32_bf16 v[70:73], v[10:13], v[196:199], v[204:207]
	v_mfma_f32_16x16x32_bf16 v[78:81], v[14:17], v[208:211], v[70:73]
	v_mfma_f32_16x16x32_bf16 v[70:73], v[180:183], v[196:199], v[98:101]
	v_mfma_f32_16x16x32_bf16 v[70:73], v[144:147], v[208:211], v[70:73]
	s_barrier
;   #define LDA(dst,b,h) for(int m=0;m<4;++m)for(int k=0;k<2;++k) \
;     dst[m][k]=*reinterpret_cast<const bf16x8*>((char*)SA(b,h)+lds_byte(wr*64+m*16+fr,k*32+fq*8))
;   #define LDB(dst,b,h) for(int n=0;n<2;++n)for(int k=0;k<2;++k) \
;     dst[n][k]=*reinterpret_cast<const bf16x8*>((char*)SB(b,h)+lds_byte(wc*32+n*16+fr,k*32+fq*8))
;   #define MMA(ai,bj,At,Bt_) do{__builtin_amdgcn_s_setprio(1); \
;     for(int m=0;m<4;++m)for(int n=0;n<2;++n)for(int k=0;k<2;++k) \
;       acc[ai][bj][m][n]=__builtin_amdgcn_mfma_f32_16x16x32_bf16(Bt_[n][k],At[m][k],acc[ai][bj][m][n],0,0,0); \
;     __builtin_amdgcn_s_setprio(0);}while(0)
;   #define WAIT_V(n) asm volatile("s_waitcnt vmcnt(" #n ")":::"memory")
;   #define WAIT_L(n) asm volatile("s_waitcnt lgkmcnt(" #n ")":::"memory")
;   #define BAR __builtin_amdgcn_s_barrier()
; template <bool TWO, class MID> ...
;     ...
;   { LDB(B0,1,0); LDA(At,1,0); WAIT_V(2); BAR; WAIT_L(0); MMA(0,0,At,B0); BAR;
;     LDB(B1,1,1); WAIT_V(0); BAR; WAIT_L(0); MMA(0,1,At,B1); BAR;
;     LDA(At,1,1); BAR; WAIT_L(0); MMA(1,0,At,B0); MMA(1,1,At,B1); BAR; }
;   if(wr==0)BAR;
	s_setprio 0
	ds_read_b128 v[130:133], v143
	ds_read_b128 v[148:151], v143 offset:1024
	ds_read_b128 v[204:207], v143 offset:2048
	ds_read_b128 v[220:223], v143 offset:3072
	s_waitcnt vmcnt(0)
	s_setprio 1
	s_barrier
	s_waitcnt lgkmcnt(0)
	v_mfma_f32_16x16x32_bf16 v[98:101], v[130:133], v[26:29], v[212:215]
	v_mfma_f32_16x16x32_bf16 v[26:29], v[204:207], v[26:29], v[90:93]
	v_mfma_f32_16x16x32_bf16 v[114:117], v[220:223], v[30:33], v[26:29]
	v_mfma_f32_16x16x32_bf16 v[26:29], v[130:133], v[42:45], v[168:171]
	v_mfma_f32_16x16x32_bf16 v[106:109], v[148:151], v[46:49], v[26:29]
	v_mfma_f32_16x16x32_bf16 v[26:29], v[204:207], v[42:45], v[82:85]
	v_mfma_f32_16x16x32_bf16 v[122:125], v[148:151], v[30:33], v[98:101]
	v_mfma_f32_16x16x32_bf16 v[98:101], v[220:223], v[46:49], v[26:29]
	v_mfma_f32_16x16x32_bf16 v[26:29], v[130:133], v[184:187], v[172:175]
	v_mfma_f32_16x16x32_bf16 v[90:93], v[148:151], v[188:191], v[26:29]
	v_mfma_f32_16x16x32_bf16 v[26:29], v[204:207], v[184:187], v[74:77]
	v_mfma_f32_16x16x32_bf16 v[82:85], v[220:223], v[188:191], v[26:29]
	v_mfma_f32_16x16x32_bf16 v[26:29], v[130:133], v[196:199], v[176:179]
	v_mfma_f32_16x16x32_bf16 v[74:77], v[148:151], v[208:211], v[26:29]
	v_mfma_f32_16x16x32_bf16 v[26:29], v[204:207], v[196:199], v[66:69]
	v_mfma_f32_16x16x32_bf16 v[66:69], v[220:223], v[208:211], v[26:29]
	s_barrier
	s_setprio 0
	ds_read_b128 v[168:171], v141 offset:49152
	ds_read_b128 v[140:143], v141 offset:50176
	ds_read_b128 v[172:175], v139 offset:49152
	ds_read_b128 v[176:179], v139 offset:50176
	ds_read_b128 v[184:187], v137 offset:49152
	ds_read_b128 v[136:139], v137 offset:50176
	ds_read_b128 v[188:191], v135 offset:49152
	ds_read_b128 v[196:199], v135 offset:50176
	s_setprio 1
	s_barrier
	s_waitcnt lgkmcnt(0)
	v_mfma_f32_16x16x32_bf16 v[26:29], v[10:13], v[168:171], v[62:65]
	v_mfma_f32_16x16x32_bf16 v[62:65], v[14:17], v[140:143], v[26:29]
	v_mfma_f32_16x16x32_bf16 v[26:29], v[180:183], v[168:171], v[58:61]
	v_mfma_f32_16x16x32_bf16 v[58:61], v[144:147], v[140:143], v[26:29]
	v_mfma_f32_16x16x32_bf16 v[26:29], v[10:13], v[172:175], v[54:57]
	v_mfma_f32_16x16x32_bf16 v[46:49], v[14:17], v[176:179], v[26:29]
	v_mfma_f32_16x16x32_bf16 v[26:29], v[180:183], v[172:175], v[50:53]
	v_mfma_f32_16x16x32_bf16 v[42:45], v[144:147], v[176:179], v[26:29]
	v_mfma_f32_16x16x32_bf16 v[26:29], v[10:13], v[184:187], v[200:203]
	v_mfma_f32_16x16x32_bf16 v[10:13], v[10:13], v[188:191], v[38:41]
	v_mfma_f32_16x16x32_bf16 v[30:33], v[14:17], v[136:139], v[26:29]
	v_mfma_f32_16x16x32_bf16 v[26:29], v[180:183], v[184:187], v[216:219]
	v_mfma_f32_16x16x32_bf16 v[14:17], v[14:17], v[196:199], v[10:13]
	v_mfma_f32_16x16x32_bf16 v[10:13], v[180:183], v[188:191], v[34:37]
	v_mfma_f32_16x16x32_bf16 v[26:29], v[144:147], v[136:139], v[26:29]
	v_mfma_f32_16x16x32_bf16 v[10:13], v[144:147], v[196:199], v[10:13]
	s_setprio 0
	s_setprio 1
	v_mfma_f32_16x16x32_bf16 v[34:37], v[130:133], v[168:171], v[152:155]
	v_mfma_f32_16x16x32_bf16 v[54:57], v[148:151], v[140:143], v[34:37]
	v_mfma_f32_16x16x32_bf16 v[34:37], v[204:207], v[168:171], v[156:159]
	v_mfma_f32_16x16x32_bf16 v[18:21], v[204:207], v[172:175], v[18:21]
	v_mfma_f32_16x16x32_bf16 v[50:53], v[220:223], v[140:143], v[34:37]
	v_mfma_f32_16x16x32_bf16 v[22:25], v[130:133], v[172:175], v[22:25]
	v_mfma_f32_16x16x32_bf16 v[34:37], v[220:223], v[176:179], v[18:21]
	v_mfma_f32_16x16x32_bf16 v[18:21], v[130:133], v[184:187], v[160:163]
	v_mfma_f32_16x16x32_bf16 v[38:41], v[148:151], v[176:179], v[22:25]
	v_mfma_f32_16x16x32_bf16 v[22:25], v[148:151], v[136:139], v[18:21]
	v_mfma_f32_16x16x32_bf16 v[18:21], v[204:207], v[184:187], v[164:167]
	v_mfma_f32_16x16x32_bf16 v[6:9], v[130:133], v[188:191], v[6:9]
	v_mfma_f32_16x16x32_bf16 v[2:5], v[204:207], v[188:191], v[2:5]
	v_mfma_f32_16x16x32_bf16 v[18:21], v[220:223], v[136:139], v[18:21]
	v_mfma_f32_16x16x32_bf16 v[6:9], v[148:151], v[196:199], v[6:9]
	v_mfma_f32_16x16x32_bf16 v[2:5], v[220:223], v[196:199], v[2:5]
	s_setprio 0
	v_cmp_gt_u32_e32 vcc, s30, v1
	s_barrier
	s_and_saveexec_b64 s[4:5], vcc
	s_cbranch_execz .LBB0_565
	s_barrier

;   #define LDA(dst,b,h) for(int m=0;m<4;++m)for(int k=0;k<2;++k) \
;     dst[m][k]=*reinterpret_cast<const bf16x8*>((char*)SA(b,h)+lds_byte(wr*64+m*16+fr,k*32+fq*8))
;   #define LDB(dst,b,h) for(int n=0;n<2;++n)for(int k=0;k<2;++k) \
;     dst[n][k]=*reinterpret_cast<const bf16x8*>((char*)SB(b,h)+lds_byte(wc*32+n*16+fr,k*32+fq*8))
;   #define MMA(ai,bj,At,Bt_) do{__builtin_amdgcn_s_setprio(1); \
;     for(int m=0;m<4;++m)for(int n=0;n<2;++n)for(int k=0;k<2;++k) \
;       acc[ai][bj][m][n]=__builtin_amdgcn_mfma_f32_16x16x32_bf16(Bt_[n][k],At[m][k],acc[ai][bj][m][n],0,0,0); \
;     __builtin_amdgcn_s_setprio(0);}while(0)
;   #define WAIT_V(n) asm volatile("s_waitcnt vmcnt(" #n ")":::"memory")
;   #define WAIT_L(n) asm volatile("s_waitcnt lgkmcnt(" #n ")":::"memory")
;   #define BAR __builtin_amdgcn_s_barrier()
;   #define SCHED __builtin_amdgcn_sched_barrier(0)
; template <bool TWO, class MID> ...
;     ...
;     LDB(B0,0,0); SCHED; LDA(At,0,0); STAGE_A(SA(1,1),1,t+1);
;     WAIT_L(8); BAR; WAIT_L(0); MMA(0,0,At,B0); BAR; SCHED;
;     LDB(B1,0,1); STAGE_B(SB(0,0),0,t+2);
;     BAR; WAIT_L(0); MMA(0,1,At,B1); BAR;
;     LDA(At,0,1); STAGE_A(SA(0,0),0,t+2);
;     BAR; WAIT_L(0); MMA(1,0,At,B0); BAR; SCHED;
;     STAGE_B(SB(0,1),1,t+2);
;     WAIT_V(6); BAR; MMA(1,1,At,B1); BAR;
.LBB0_620:
	ds_read_b128 v[166:169], v149
	ds_read_b128 v[170:173], v149 offset:1024
	ds_read_b128 v[174:177], v149 offset:2048
	ds_read_b128 v[178:181], v149 offset:3072
	ds_read_b128 v[182:185], v141
	ds_read_b128 v[186:189], v141 offset:1024
	ds_read_b128 v[190:193], v139
	ds_read_b128 v[196:199], v139 offset:1024
	ds_read_b128 v[200:203], v137
	ds_read_b128 v[204:207], v137 offset:1024
	ds_read_b128 v[208:211], v135
	ds_read_b128 v[212:215], v135 offset:1024
	s_add_u32 s15, s0, s16
	s_addc_u32 s18, s1, s17
	s_add_u32 s24, s15, 0x10200080
	s_addc_u32 s25, s18, 0
	s_add_u32 m0, s98, 0xc000
	global_load_lds_dwordx4 v132, s[24:25]
	s_add_u32 m0, s98, 0xe000
	global_load_lds_dwordx4 v130, s[24:25]
	s_waitcnt lgkmcnt(8)
	s_setprio 1
	s_barrier
	s_waitcnt lgkmcnt(0)
	v_mfma_f32_16x16x32_bf16 v[126:129], v[166:169], v[182:185], v[126:129]
	v_mfma_f32_16x16x32_bf16 v[122:125], v[174:177], v[182:185], v[122:125]
	v_mfma_f32_16x16x32_bf16 v[118:121], v[166:169], v[190:193], v[118:121]
	v_mfma_f32_16x16x32_bf16 v[114:117], v[174:177], v[190:193], v[114:117]
	v_mfma_f32_16x16x32_bf16 v[110:113], v[166:169], v[200:203], v[110:113]
	v_mfma_f32_16x16x32_bf16 v[106:109], v[174:177], v[200:203], v[106:109]
	v_mfma_f32_16x16x32_bf16 v[102:105], v[166:169], v[208:211], v[102:105]
	v_mfma_f32_16x16x32_bf16 v[98:101], v[174:177], v[208:211], v[98:101]
	v_mfma_f32_16x16x32_bf16 v[126:129], v[170:173], v[186:189], v[126:129]
	v_mfma_f32_16x16x32_bf16 v[122:125], v[178:181], v[186:189], v[122:125]
	v_mfma_f32_16x16x32_bf16 v[118:121], v[170:173], v[196:199], v[118:121]
	v_mfma_f32_16x16x32_bf16 v[114:117], v[178:181], v[196:199], v[114:117]
	v_mfma_f32_16x16x32_bf16 v[110:113], v[170:173], v[204:207], v[110:113]
	v_mfma_f32_16x16x32_bf16 v[106:109], v[178:181], v[204:207], v[106:109]
	v_mfma_f32_16x16x32_bf16 v[102:105], v[170:173], v[212:215], v[102:105]
	v_mfma_f32_16x16x32_bf16 v[98:101], v[178:181], v[212:215], v[98:101]
	s_barrier
	s_setprio 0
	s_add_u32 s19, s0, s4
	ds_read_b128 v[216:219], v147
	ds_read_b128 v[220:223], v147 offset:1024
	ds_read_b128 v[224:227], v147 offset:2048
	ds_read_b128 v[228:231], v147 offset:3072
	s_addc_u32 s24, s1, s5
	s_add_u32 s26, s19, 0x5c00100
	s_addc_u32 s27, s24, 0
	s_add_u32 m0, s98, 0x10000
	global_load_lds_dwordx4 v132, s[26:27]
	s_add_u32 m0, s98, 0x12000
	global_load_lds_dwordx4 v130, s[26:27]
	s_setprio 1
	s_barrier
	s_waitcnt lgkmcnt(0)
	v_mfma_f32_16x16x32_bf16 v[94:97], v[216:219], v[182:185], v[94:97]
	v_mfma_f32_16x16x32_bf16 v[90:93], v[224:227], v[182:185], v[90:93]
	v_mfma_f32_16x16x32_bf16 v[86:89], v[216:219], v[190:193], v[86:89]
	v_mfma_f32_16x16x32_bf16 v[82:85], v[224:227], v[190:193], v[82:85]
	v_mfma_f32_16x16x32_bf16 v[78:81], v[216:219], v[200:203], v[78:81]
	v_mfma_f32_16x16x32_bf16 v[74:77], v[224:227], v[200:203], v[74:77]
	v_mfma_f32_16x16x32_bf16 v[70:73], v[216:219], v[208:211], v[70:73]
	v_mfma_f32_16x16x32_bf16 v[66:69], v[224:227], v[208:211], v[66:69]
	v_mfma_f32_16x16x32_bf16 v[94:97], v[220:223], v[186:189], v[94:97]
	v_mfma_f32_16x16x32_bf16 v[90:93], v[228:231], v[186:189], v[90:93]
	v_mfma_f32_16x16x32_bf16 v[86:89], v[220:223], v[196:199], v[86:89]
	v_mfma_f32_16x16x32_bf16 v[82:85], v[228:231], v[196:199], v[82:85]
	v_mfma_f32_16x16x32_bf16 v[78:81], v[220:223], v[204:207], v[78:81]
	v_mfma_f32_16x16x32_bf16 v[74:77], v[228:231], v[204:207], v[74:77]
	v_mfma_f32_16x16x32_bf16 v[70:73], v[220:223], v[212:215], v[70:73]
	v_mfma_f32_16x16x32_bf16 v[66:69], v[228:231], v[212:215], v[66:69]
	s_barrier
	s_setprio 0
	ds_read_b128 v[182:185], v141 offset:16384
	ds_read_b128 v[186:189], v141 offset:17408
	ds_read_b128 v[190:193], v139 offset:16384
	ds_read_b128 v[196:199], v139 offset:17408
	ds_read_b128 v[200:203], v137 offset:16384
	ds_read_b128 v[204:207], v137 offset:17408
	ds_read_b128 v[208:211], v135 offset:16384
	ds_read_b128 v[212:215], v135 offset:17408
	s_add_u32 s26, s15, 0x10000100
	s_addc_u32 s27, s18, 0
	s_add_u32 m0, s98, 0x0
	global_load_lds_dwordx4 v132, s[26:27]
	s_add_u32 m0, s98, 0x2000
	global_load_lds_dwordx4 v130, s[26:27]
	s_setprio 1
	s_barrier
	s_waitcnt lgkmcnt(0)
	v_mfma_f32_16x16x32_bf16 v[62:65], v[166:169], v[182:185], v[62:65]
	v_mfma_f32_16x16x32_bf16 v[58:61], v[174:177], v[182:185], v[58:61]
	v_mfma_f32_16x16x32_bf16 v[54:57], v[166:169], v[190:193], v[54:57]
	v_mfma_f32_16x16x32_bf16 v[50:53], v[174:177], v[190:193], v[50:53]
	v_mfma_f32_16x16x32_bf16 v[46:49], v[166:169], v[200:203], v[46:49]
	v_mfma_f32_16x16x32_bf16 v[42:45], v[174:177], v[200:203], v[42:45]
	v_mfma_f32_16x16x32_bf16 v[38:41], v[166:169], v[208:211], v[38:41]
	v_mfma_f32_16x16x32_bf16 v[34:37], v[174:177], v[208:211], v[34:37]
	v_mfma_f32_16x16x32_bf16 v[62:65], v[170:173], v[186:189], v[62:65]
	v_mfma_f32_16x16x32_bf16 v[58:61], v[178:181], v[186:189], v[58:61]
	v_mfma_f32_16x16x32_bf16 v[54:57], v[170:173], v[196:199], v[54:57]
	v_mfma_f32_16x16x32_bf16 v[50:53], v[178:181], v[196:199], v[50:53]
	v_mfma_f32_16x16x32_bf16 v[46:49], v[170:173], v[204:207], v[46:49]
	v_mfma_f32_16x16x32_bf16 v[42:45], v[178:181], v[204:207], v[42:45]
	v_mfma_f32_16x16x32_bf16 v[38:41], v[170:173], v[212:215], v[38:41]
	v_mfma_f32_16x16x32_bf16 v[34:37], v[178:181], v[212:215], v[34:37]
	s_barrier
	s_setprio 0
	s_add_u32 s26, s19, 0x5e00100
	s_addc_u32 s27, s24, 0
	s_add_u32 m0, s98, 0x14000
	global_load_lds_dwordx4 v132, s[26:27]
	s_add_u32 m0, s98, 0x16000
	global_load_lds_dwordx4 v130, s[26:27]
	s_waitcnt vmcnt(6)
	s_setprio 1
	s_barrier
;   #define LDA(dst,b,h) for(int m=0;m<4;++m)for(int k=0;k<2;++k) \
;     dst[m][k]=*reinterpret_cast<const bf16x8*>((char*)SA(b,h)+lds_byte(wr*64+m*16+fr,k*32+fq*8))
;   #define LDB(dst,b,h) for(int n=0;n<2;++n)for(int k=0;k<2;++k) \
;     dst[n][k]=*reinterpret_cast<const bf16x8*>((char*)SB(b,h)+lds_byte(wc*32+n*16+fr,k*32+fq*8))
;   #define MMA(ai,bj,At,Bt_) do{__builtin_amdgcn_s_setprio(1); \
;     for(int m=0;m<4;++m)for(int n=0;n<2;++n)for(int k=0;k<2;++k) \
;       acc[ai][bj][m][n]=__builtin_amdgcn_mfma_f32_16x16x32_bf16(Bt_[n][k],At[m][k],acc[ai][bj][m][n],0,0,0); \
;     __builtin_amdgcn_s_setprio(0);}while(0)
;   #define WAIT_V(n) asm volatile("s_waitcnt vmcnt(" #n ")":::"memory")
;   #define WAIT_L(n) asm volatile("s_waitcnt lgkmcnt(" #n ")":::"memory")
;   #define BAR __builtin_amdgcn_s_barrier()
;   #define SCHED __builtin_amdgcn_sched_barrier(0)
; template <bool TWO, class MID> ...
;     ...
;     WAIT_V(6); BAR; MMA(1,1,At,B1); BAR;
;     LDB(B0,1,0); SCHED; LDA(At,1,0); STAGE_A(SA(0,1),1,t+2);
;     WAIT_L(8); BAR; WAIT_L(0); MMA(0,0,At,B0); BAR; SCHED;
;     LDB(B1,1,1); STAGE_B(SB(1,0),0,t+3);
;     BAR; WAIT_L(0); MMA(0,1,At,B1); BAR;
;     LDA(At,1,1); STAGE_A(SA(1,0),0,t+3);
;     BAR; WAIT_L(0); MMA(1,0,At,B0); BAR; SCHED;
	v_mfma_f32_16x16x32_bf16 v[30:33], v[216:219], v[182:185], v[30:33]
	v_mfma_f32_16x16x32_bf16 v[26:29], v[224:227], v[182:185], v[26:29]
	v_mfma_f32_16x16x32_bf16 v[22:25], v[216:219], v[190:193], v[22:25]
	v_mfma_f32_16x16x32_bf16 v[18:21], v[224:227], v[190:193], v[18:21]
	v_mfma_f32_16x16x32_bf16 v[14:17], v[216:219], v[200:203], v[14:17]
	v_mfma_f32_16x16x32_bf16 v[10:13], v[224:227], v[200:203], v[10:13]
	v_mfma_f32_16x16x32_bf16 v[6:9], v[216:219], v[208:211], v[6:9]
	v_mfma_f32_16x16x32_bf16 v[2:5], v[224:227], v[208:211], v[2:5]
	v_mfma_f32_16x16x32_bf16 v[30:33], v[220:223], v[186:189], v[30:33]
	v_mfma_f32_16x16x32_bf16 v[26:29], v[228:231], v[186:189], v[26:29]
	v_mfma_f32_16x16x32_bf16 v[22:25], v[220:223], v[196:199], v[22:25]
	v_mfma_f32_16x16x32_bf16 v[18:21], v[228:231], v[196:199], v[18:21]
	v_mfma_f32_16x16x32_bf16 v[14:17], v[220:223], v[204:207], v[14:17]
	v_mfma_f32_16x16x32_bf16 v[10:13], v[228:231], v[204:207], v[10:13]
	v_mfma_f32_16x16x32_bf16 v[6:9], v[220:223], v[212:215], v[6:9]
	v_mfma_f32_16x16x32_bf16 v[2:5], v[228:231], v[212:215], v[2:5]
	s_barrier
	s_setprio 0
	ds_read_b128 v[166:169], v145
	ds_read_b128 v[170:173], v145 offset:1024
	ds_read_b128 v[174:177], v145 offset:2048
	ds_read_b128 v[178:181], v145 offset:3072
	ds_read_b128 v[182:185], v141 offset:32768
	ds_read_b128 v[186:189], v141 offset:33792
	ds_read_b128 v[190:193], v139 offset:32768
	ds_read_b128 v[196:199], v139 offset:33792
	ds_read_b128 v[200:203], v137 offset:32768
	ds_read_b128 v[204:207], v137 offset:33792
	ds_read_b128 v[208:211], v135 offset:32768
	ds_read_b128 v[212:215], v135 offset:33792
	s_add_u32 s26, s15, 0x10200100
	s_addc_u32 s27, s18, 0
	s_add_u32 m0, s98, 0x4000
	global_load_lds_dwordx4 v132, s[26:27]
	s_add_u32 m0, s98, 0x6000
	global_load_lds_dwordx4 v130, s[26:27]
	s_waitcnt lgkmcnt(8)
	s_setprio 1
	s_barrier
	s_waitcnt lgkmcnt(0)
	v_mfma_f32_16x16x32_bf16 v[126:129], v[166:169], v[182:185], v[126:129]
	v_mfma_f32_16x16x32_bf16 v[122:125], v[174:177], v[182:185], v[122:125]
	v_mfma_f32_16x16x32_bf16 v[118:121], v[166:169], v[190:193], v[118:121]
	v_mfma_f32_16x16x32_bf16 v[114:117], v[174:177], v[190:193], v[114:117]
	v_mfma_f32_16x16x32_bf16 v[110:113], v[166:169], v[200:203], v[110:113]
	v_mfma_f32_16x16x32_bf16 v[106:109], v[174:177], v[200:203], v[106:109]
	v_mfma_f32_16x16x32_bf16 v[102:105], v[166:169], v[208:211], v[102:105]
	v_mfma_f32_16x16x32_bf16 v[98:101], v[174:177], v[208:211], v[98:101]
	v_mfma_f32_16x16x32_bf16 v[126:129], v[170:173], v[186:189], v[126:129]
	v_mfma_f32_16x16x32_bf16 v[122:125], v[178:181], v[186:189], v[122:125]
	v_mfma_f32_16x16x32_bf16 v[118:121], v[170:173], v[196:199], v[118:121]
	v_mfma_f32_16x16x32_bf16 v[114:117], v[178:181], v[196:199], v[114:117]
	v_mfma_f32_16x16x32_bf16 v[110:113], v[170:173], v[204:207], v[110:113]
	v_mfma_f32_16x16x32_bf16 v[106:109], v[178:181], v[204:207], v[106:109]
	v_mfma_f32_16x16x32_bf16 v[102:105], v[170:173], v[212:215], v[102:105]
	v_mfma_f32_16x16x32_bf16 v[98:101], v[178:181], v[212:215], v[98:101]
	s_barrier
	s_setprio 0
	ds_read_b128 v[216:219], v143
	ds_read_b128 v[220:223], v143 offset:1024
	ds_read_b128 v[224:227], v143 offset:2048
	ds_read_b128 v[228:231], v143 offset:3072
	s_add_u32 s26, s19, 0x5c00180
	s_addc_u32 s27, s24, 0
	s_add_u32 m0, s98, 0x18000
	global_load_lds_dwordx4 v132, s[26:27]
	s_add_u32 m0, s98, 0x1a000
	global_load_lds_dwordx4 v130, s[26:27]
	s_setprio 1
	s_barrier
	s_waitcnt lgkmcnt(0)
	v_mfma_f32_16x16x32_bf16 v[94:97], v[216:219], v[182:185], v[94:97]
	v_mfma_f32_16x16x32_bf16 v[90:93], v[224:227], v[182:185], v[90:93]
	v_mfma_f32_16x16x32_bf16 v[86:89], v[216:219], v[190:193], v[86:89]
	v_mfma_f32_16x16x32_bf16 v[82:85], v[224:227], v[190:193], v[82:85]
	v_mfma_f32_16x16x32_bf16 v[78:81], v[216:219], v[200:203], v[78:81]
	v_mfma_f32_16x16x32_bf16 v[74:77], v[224:227], v[200:203], v[74:77]
	v_mfma_f32_16x16x32_bf16 v[70:73], v[216:219], v[208:211], v[70:73]
	v_mfma_f32_16x16x32_bf16 v[66:69], v[224:227], v[208:211], v[66:69]
	v_mfma_f32_16x16x32_bf16 v[94:97], v[220:223], v[186:189], v[94:97]
	v_mfma_f32_16x16x32_bf16 v[90:93], v[228:231], v[186:189], v[90:93]
	v_mfma_f32_16x16x32_bf16 v[86:89], v[220:223], v[196:199], v[86:89]
	v_mfma_f32_16x16x32_bf16 v[82:85], v[228:231], v[196:199], v[82:85]
	v_mfma_f32_16x16x32_bf16 v[78:81], v[220:223], v[204:207], v[78:81]
	v_mfma_f32_16x16x32_bf16 v[74:77], v[228:231], v[204:207], v[74:77]
	v_mfma_f32_16x16x32_bf16 v[70:73], v[220:223], v[212:215], v[70:73]
	v_mfma_f32_16x16x32_bf16 v[66:69], v[228:231], v[212:215], v[66:69]
	s_barrier
	s_setprio 0
	ds_read_b128 v[182:185], v141 offset:49152
	ds_read_b128 v[186:189], v141 offset:50176
	ds_read_b128 v[190:193], v139 offset:49152
	ds_read_b128 v[196:199], v139 offset:50176
	ds_read_b128 v[200:203], v137 offset:49152
	ds_read_b128 v[204:207], v137 offset:50176
	ds_read_b128 v[208:211], v135 offset:49152
	ds_read_b128 v[212:215], v135 offset:50176
	s_add_u32 s26, s15, 0x10000180
	s_addc_u32 s27, s18, 0
	s_add_u32 m0, s98, 0x8000
	global_load_lds_dwordx4 v132, s[26:27]
	s_add_u32 m0, s98, 0xa000
	global_load_lds_dwordx4 v130, s[26:27]
	s_setprio 1
	s_barrier
;   #define LDA(dst,b,h) for(int m=0;m<4;++m)for(int k=0;k<2;++k) \
;     dst[m][k]=*reinterpret_cast<const bf16x8*>((char*)SA(b,h)+lds_byte(wr*64+m*16+fr,k*32+fq*8))
;   #define LDB(dst,b,h) for(int n=0;n<2;++n)for(int k=0;k<2;++k) \
;     dst[n][k]=*reinterpret_cast<const bf16x8*>((char*)SB(b,h)+lds_byte(wc*32+n*16+fr,k*32+fq*8))
;   #define MMA(ai,bj,At,Bt_) do{__builtin_amdgcn_s_setprio(1); \
;     for(int m=0;m<4;++m)for(int n=0;n<2;++n)for(int k=0;k<2;++k) \
;       acc[ai][bj][m][n]=__builtin_amdgcn_mfma_f32_16x16x32_bf16(Bt_[n][k],At[m][k],acc[ai][bj][m][n],0,0,0); \
;     __builtin_amdgcn_s_setprio(0);}while(0)
;   #define WAIT_V(n) asm volatile("s_waitcnt vmcnt(" #n ")":::"memory")
;   #define WAIT_L(n) asm volatile("s_waitcnt lgkmcnt(" #n ")":::"memory")
;   #define BAR __builtin_amdgcn_s_barrier()
;   #define SCHED __builtin_amdgcn_sched_barrier(0)
; template <bool TWO, class MID> ...
;     ...
;     BAR; WAIT_L(0); MMA(1,0,At,B0); BAR; SCHED;
;     STAGE_B(SB(1,1),1,t+3);
;     WAIT_V(6); BAR; MMA(1,1,At,B1); BAR;
;   }
;   { LDB(B0,0,0); LDA(At,0,0); STAGE_A(SA(1,1),1,nt-1);
;     BAR; WAIT_L(0); MMA(0,0,At,B0); BAR;
;     LDB(B1,0,1); BAR; WAIT_L(0); MMA(0,1,At,B1); BAR;
	s_waitcnt lgkmcnt(0)
	v_mfma_f32_16x16x32_bf16 v[62:65], v[166:169], v[182:185], v[62:65]
	v_mfma_f32_16x16x32_bf16 v[58:61], v[174:177], v[182:185], v[58:61]
	v_mfma_f32_16x16x32_bf16 v[54:57], v[166:169], v[190:193], v[54:57]
	v_mfma_f32_16x16x32_bf16 v[50:53], v[174:177], v[190:193], v[50:53]
	v_mfma_f32_16x16x32_bf16 v[46:49], v[166:169], v[200:203], v[46:49]
	v_mfma_f32_16x16x32_bf16 v[42:45], v[174:177], v[200:203], v[42:45]
	v_mfma_f32_16x16x32_bf16 v[38:41], v[166:169], v[208:211], v[38:41]
	v_mfma_f32_16x16x32_bf16 v[34:37], v[174:177], v[208:211], v[34:37]
	v_mfma_f32_16x16x32_bf16 v[62:65], v[170:173], v[186:189], v[62:65]
	v_mfma_f32_16x16x32_bf16 v[58:61], v[178:181], v[186:189], v[58:61]
	v_mfma_f32_16x16x32_bf16 v[54:57], v[170:173], v[196:199], v[54:57]
	v_mfma_f32_16x16x32_bf16 v[50:53], v[178:181], v[196:199], v[50:53]
	v_mfma_f32_16x16x32_bf16 v[46:49], v[170:173], v[204:207], v[46:49]
	v_mfma_f32_16x16x32_bf16 v[42:45], v[178:181], v[204:207], v[42:45]
	v_mfma_f32_16x16x32_bf16 v[38:41], v[170:173], v[212:215], v[38:41]
	v_mfma_f32_16x16x32_bf16 v[34:37], v[178:181], v[212:215], v[34:37]
	s_barrier
	s_setprio 0
	s_add_u32 s18, s19, 0x5e00180
	s_addc_u32 s19, s24, 0
	s_add_u32 m0, s98, 0x1c000
	global_load_lds_dwordx4 v132, s[18:19]
	s_add_u32 m0, s98, 0x1e000
	global_load_lds_dwordx4 v130, s[18:19]
	s_waitcnt vmcnt(6)
	s_setprio 1
	s_barrier
	v_mfma_f32_16x16x32_bf16 v[30:33], v[216:219], v[182:185], v[30:33]
	v_mfma_f32_16x16x32_bf16 v[26:29], v[224:227], v[182:185], v[26:29]
	v_mfma_f32_16x16x32_bf16 v[22:25], v[216:219], v[190:193], v[22:25]
	v_mfma_f32_16x16x32_bf16 v[18:21], v[224:227], v[190:193], v[18:21]
	v_mfma_f32_16x16x32_bf16 v[14:17], v[216:219], v[200:203], v[14:17]
	v_mfma_f32_16x16x32_bf16 v[10:13], v[224:227], v[200:203], v[10:13]
	v_mfma_f32_16x16x32_bf16 v[6:9], v[216:219], v[208:211], v[6:9]
	v_mfma_f32_16x16x32_bf16 v[2:5], v[224:227], v[208:211], v[2:5]
	v_mfma_f32_16x16x32_bf16 v[30:33], v[220:223], v[186:189], v[30:33]
	v_mfma_f32_16x16x32_bf16 v[26:29], v[228:231], v[186:189], v[26:29]
	v_mfma_f32_16x16x32_bf16 v[22:25], v[220:223], v[196:199], v[22:25]
	v_mfma_f32_16x16x32_bf16 v[18:21], v[228:231], v[196:199], v[18:21]
	v_mfma_f32_16x16x32_bf16 v[14:17], v[220:223], v[204:207], v[14:17]
	v_mfma_f32_16x16x32_bf16 v[10:13], v[228:231], v[204:207], v[10:13]
	v_mfma_f32_16x16x32_bf16 v[6:9], v[220:223], v[212:215], v[6:9]
	v_mfma_f32_16x16x32_bf16 v[2:5], v[228:231], v[212:215], v[2:5]
	s_setprio 0
	s_add_i32 s14, s14, 2
	s_add_u32 s0, s0, 0x100
	s_addc_u32 s1, s1, 0
	s_cmpk_lt_u32 s14, 0x7c
	s_barrier
	s_cbranch_scc1 .LBB0_620
	ds_read_b128 v[152:155], v149
	ds_read_b128 v[156:159], v149 offset:1024
	ds_read_b128 v[160:163], v149 offset:2048
	ds_read_b128 v[164:167], v149 offset:3072
	ds_read_b128 v[168:171], v141
	ds_read_b128 v[172:175], v141 offset:1024
	ds_read_b128 v[176:179], v139
	ds_read_b128 v[180:183], v139 offset:1024
	ds_read_b128 v[184:187], v137
	ds_read_b128 v[188:191], v137 offset:1024
	ds_read_b128 v[196:199], v135
	ds_read_b128 v[200:203], v135 offset:1024
	s_add_u32 s0, s12, 0x203f80
	s_addc_u32 s1, s13, 0
	v_lshl_add_u64 v[132:133], s[0:1], 0, v[132:133]
	v_readfirstlane_b32 s12, v148
	s_mov_b32 m0, s12
	global_load_lds_dwordx4 v[132:133], off
	v_lshl_add_u64 v[130:131], s[0:1], 0, v[130:131]
	v_readfirstlane_b32 s0, v150
	s_mov_b32 m0, s0
	global_load_lds_dwordx4 v[130:131], off
	s_setprio 1
	s_barrier
	s_waitcnt lgkmcnt(0)
	v_mfma_f32_16x16x32_bf16 v[126:129], v[152:155], v[168:171], v[126:129]
	v_mfma_f32_16x16x32_bf16 v[122:125], v[160:163], v[168:171], v[122:125]
	v_mfma_f32_16x16x32_bf16 v[118:121], v[152:155], v[176:179], v[118:121]
	v_mfma_f32_16x16x32_bf16 v[114:117], v[160:163], v[176:179], v[114:117]
	v_mfma_f32_16x16x32_bf16 v[102:105], v[152:155], v[196:199], v[102:105]
	v_mfma_f32_16x16x32_bf16 v[98:101], v[160:163], v[196:199], v[98:101]
	v_mfma_f32_16x16x32_bf16 v[126:129], v[156:159], v[172:175], v[126:129]
	v_mfma_f32_16x16x32_bf16 v[122:125], v[164:167], v[172:175], v[122:125]
	v_mfma_f32_16x16x32_bf16 v[118:121], v[156:159], v[180:183], v[118:121]
	v_mfma_f32_16x16x32_bf16 v[114:117], v[164:167], v[180:183], v[114:117]
	v_mfma_f32_16x16x32_bf16 v[110:113], v[152:155], v[184:187], v[110:113]
	v_mfma_f32_16x16x32_bf16 v[106:109], v[160:163], v[184:187], v[106:109]
	v_mfma_f32_16x16x32_bf16 v[102:105], v[156:159], v[200:203], v[102:105]
	v_mfma_f32_16x16x32_bf16 v[98:101], v[164:167], v[200:203], v[98:101]
	v_mfma_f32_16x16x32_bf16 v[130:133], v[156:159], v[188:191], v[110:113]
	v_mfma_f32_16x16x32_bf16 v[148:151], v[164:167], v[188:191], v[106:109]
	s_barrier
	s_setprio 0
	s_nop 0
	ds_read_b128 v[106:109], v147
	ds_read_b128 v[110:113], v147 offset:1024
	ds_read_b128 v[204:207], v147 offset:2048
	ds_read_b128 v[208:211], v147 offset:3072
	s_setprio 1
	s_barrier
	s_waitcnt lgkmcnt(0)
	v_mfma_f32_16x16x32_bf16 v[86:89], v[106:109], v[176:179], v[86:89]
	v_mfma_f32_16x16x32_bf16 v[82:85], v[204:207], v[176:179], v[82:85]
	v_mfma_f32_16x16x32_bf16 v[70:73], v[106:109], v[196:199], v[70:73]
	v_mfma_f32_16x16x32_bf16 v[66:69], v[204:207], v[196:199], v[66:69]
	v_mfma_f32_16x16x32_bf16 v[94:97], v[106:109], v[168:171], v[94:97]
	v_mfma_f32_16x16x32_bf16 v[90:93], v[204:207], v[168:171], v[90:93]
	v_mfma_f32_16x16x32_bf16 v[86:89], v[110:113], v[180:183], v[86:89]
	v_mfma_f32_16x16x32_bf16 v[82:85], v[208:211], v[180:183], v[82:85]
	v_mfma_f32_16x16x32_bf16 v[78:81], v[106:109], v[184:187], v[78:81]
	v_mfma_f32_16x16x32_bf16 v[74:77], v[204:207], v[184:187], v[74:77]
	v_mfma_f32_16x16x32_bf16 v[70:73], v[110:113], v[200:203], v[70:73]
	v_mfma_f32_16x16x32_bf16 v[66:69], v[208:211], v[200:203], v[66:69]
	v_mfma_f32_16x16x32_bf16 v[212:215], v[110:113], v[172:175], v[94:97]
	v_mfma_f32_16x16x32_bf16 v[168:171], v[208:211], v[172:175], v[90:93]
	v_mfma_f32_16x16x32_bf16 v[172:175], v[110:113], v[188:191], v[78:81]
	v_mfma_f32_16x16x32_bf16 v[176:179], v[208:211], v[188:191], v[74:77]
	s_barrier
;   #define LDA(dst,b,h) for(int m=0;m<4;++m)for(int k=0;k<2;++k) \
;     dst[m][k]=*reinterpret_cast<const bf16x8*>((char*)SA(b,h)+lds_byte(wr*64+m*16+fr,k*32+fq*8))
;   #define LDB(dst,b,h) for(int n=0;n<2;++n)for(int k=0;k<2;++k) \
;     dst[n][k]=*reinterpret_cast<const bf16x8*>((char*)SB(b,h)+lds_byte(wc*32+n*16+fr,k*32+fq*8))
;   #define MMA(ai,bj,At,Bt_) do{__builtin_amdgcn_s_setprio(1); \
;     for(int m=0;m<4;++m)for(int n=0;n<2;++n)for(int k=0;k<2;++k) \
;       acc[ai][bj][m][n]=__builtin_amdgcn_mfma_f32_16x16x32_bf16(Bt_[n][k],At[m][k],acc[ai][bj][m][n],0,0,0); \
;     __builtin_amdgcn_s_setprio(0);}while(0)
;   #define WAIT_V(n) asm volatile("s_waitcnt vmcnt(" #n ")":::"memory")
;   #define WAIT_L(n) asm volatile("s_waitcnt lgkmcnt(" #n ")":::"memory")
;   #define BAR __builtin_amdgcn_s_barrier()
; template <bool TWO, class MID> ...
;     ...
;     LDA(At,0,1); WAIT_V(4); BAR; WAIT_L(0); MMA(1,0,At,B0); MMA(1,1,At,B1); BAR; }
;   { LDB(B0,1,0); LDA(At,1,0); WAIT_V(2); BAR; WAIT_L(0); MMA(0,0,At,B0); BAR;
	s_setprio 0
	s_nop 0
	ds_read_b128 v[74:77], v141 offset:16384
	ds_read_b128 v[78:81], v141 offset:17408
	ds_read_b128 v[90:93], v139 offset:16384
	ds_read_b128 v[94:97], v139 offset:17408
	ds_read_b128 v[180:183], v137 offset:16384
	ds_read_b128 v[184:187], v137 offset:17408
	ds_read_b128 v[188:191], v135 offset:16384
	ds_read_b128 v[196:199], v135 offset:17408
	s_waitcnt vmcnt(4)
	s_setprio 1
	s_barrier
	s_waitcnt lgkmcnt(0)
	v_mfma_f32_16x16x32_bf16 v[62:65], v[152:155], v[74:77], v[62:65]
	v_mfma_f32_16x16x32_bf16 v[58:61], v[160:163], v[74:77], v[58:61]
	v_mfma_f32_16x16x32_bf16 v[54:57], v[152:155], v[90:93], v[54:57]
	v_mfma_f32_16x16x32_bf16 v[50:53], v[160:163], v[90:93], v[50:53]
	v_mfma_f32_16x16x32_bf16 v[38:41], v[152:155], v[188:191], v[38:41]
	v_mfma_f32_16x16x32_bf16 v[34:37], v[160:163], v[188:191], v[34:37]
	v_mfma_f32_16x16x32_bf16 v[62:65], v[156:159], v[78:81], v[62:65]
	v_mfma_f32_16x16x32_bf16 v[58:61], v[164:167], v[78:81], v[58:61]
	v_mfma_f32_16x16x32_bf16 v[54:57], v[156:159], v[94:97], v[54:57]
	v_mfma_f32_16x16x32_bf16 v[50:53], v[164:167], v[94:97], v[50:53]
	v_mfma_f32_16x16x32_bf16 v[46:49], v[152:155], v[180:183], v[46:49]
	v_mfma_f32_16x16x32_bf16 v[42:45], v[160:163], v[180:183], v[42:45]
	v_mfma_f32_16x16x32_bf16 v[38:41], v[156:159], v[196:199], v[38:41]
	v_mfma_f32_16x16x32_bf16 v[34:37], v[164:167], v[196:199], v[34:37]
	v_mfma_f32_16x16x32_bf16 v[200:203], v[156:159], v[184:187], v[46:49]
	v_mfma_f32_16x16x32_bf16 v[216:219], v[164:167], v[184:187], v[42:45]
	s_setprio 0
	s_setprio 1
	v_mfma_f32_16x16x32_bf16 v[22:25], v[106:109], v[90:93], v[22:25]
	v_mfma_f32_16x16x32_bf16 v[18:21], v[204:207], v[90:93], v[18:21]
	v_mfma_f32_16x16x32_bf16 v[6:9], v[106:109], v[188:191], v[6:9]
	v_mfma_f32_16x16x32_bf16 v[2:5], v[204:207], v[188:191], v[2:5]
	v_mfma_f32_16x16x32_bf16 v[30:33], v[106:109], v[74:77], v[30:33]
	v_mfma_f32_16x16x32_bf16 v[26:29], v[204:207], v[74:77], v[26:29]
	v_mfma_f32_16x16x32_bf16 v[22:25], v[110:113], v[94:97], v[22:25]
	v_mfma_f32_16x16x32_bf16 v[18:21], v[208:211], v[94:97], v[18:21]
	v_mfma_f32_16x16x32_bf16 v[14:17], v[106:109], v[180:183], v[14:17]
	v_mfma_f32_16x16x32_bf16 v[10:13], v[204:207], v[180:183], v[10:13]
	v_mfma_f32_16x16x32_bf16 v[6:9], v[110:113], v[196:199], v[6:9]
	v_mfma_f32_16x16x32_bf16 v[2:5], v[208:211], v[196:199], v[2:5]
	v_mfma_f32_16x16x32_bf16 v[152:155], v[110:113], v[78:81], v[30:33]
	v_mfma_f32_16x16x32_bf16 v[156:159], v[208:211], v[78:81], v[26:29]
	v_mfma_f32_16x16x32_bf16 v[160:163], v[110:113], v[184:187], v[14:17]
	v_mfma_f32_16x16x32_bf16 v[164:167], v[208:211], v[184:187], v[10:13]
	s_barrier
	s_setprio 0
	s_nop 0
	ds_read_b128 v[10:13], v145
	ds_read_b128 v[14:17], v145 offset:1024
	ds_read_b128 v[180:183], v145 offset:2048
	ds_read_b128 v[144:147], v145 offset:3072
	ds_read_b128 v[26:29], v141 offset:32768
	ds_read_b128 v[30:33], v141 offset:33792
	ds_read_b128 v[42:45], v139 offset:32768
	ds_read_b128 v[46:49], v139 offset:33792
	ds_read_b128 v[184:187], v137 offset:32768
	ds_read_b128 v[188:191], v137 offset:33792
	ds_read_b128 v[196:199], v135 offset:32768
	ds_read_b128 v[204:207], v135 offset:33792
	s_waitcnt vmcnt(2)
	s_setprio 1
	s_barrier
	s_waitcnt lgkmcnt(0)
	v_mfma_f32_16x16x32_bf16 v[74:77], v[10:13], v[26:29], v[126:129]
	v_mfma_f32_16x16x32_bf16 v[126:129], v[14:17], v[30:33], v[74:77]
	v_mfma_f32_16x16x32_bf16 v[74:77], v[180:183], v[26:29], v[122:125]
	v_mfma_f32_16x16x32_bf16 v[122:125], v[144:147], v[30:33], v[74:77]
	v_mfma_f32_16x16x32_bf16 v[74:77], v[10:13], v[42:45], v[118:121]
	v_mfma_f32_16x16x32_bf16 v[110:113], v[14:17], v[46:49], v[74:77]
	v_mfma_f32_16x16x32_bf16 v[74:77], v[180:183], v[42:45], v[114:117]
	v_mfma_f32_16x16x32_bf16 v[106:109], v[144:147], v[46:49], v[74:77]
	v_mfma_f32_16x16x32_bf16 v[74:77], v[10:13], v[184:187], v[130:133]
	v_mfma_f32_16x16x32_bf16 v[94:97], v[14:17], v[188:191], v[74:77]
	v_mfma_f32_16x16x32_bf16 v[74:77], v[180:183], v[184:187], v[148:151]
	v_mfma_f32_16x16x32_bf16 v[90:93], v[144:147], v[188:191], v[74:77]
	v_mfma_f32_16x16x32_bf16 v[74:77], v[10:13], v[196:199], v[102:105]
	v_mfma_f32_16x16x32_bf16 v[78:81], v[14:17], v[204:207], v[74:77]
	v_mfma_f32_16x16x32_bf16 v[74:77], v[180:183], v[196:199], v[98:101]
	v_mfma_f32_16x16x32_bf16 v[74:77], v[144:147], v[204:207], v[74:77]
	s_barrier
;   #define LDA(dst,b,h) for(int m=0;m<4;++m)for(int k=0;k<2;++k) \
;     dst[m][k]=*reinterpret_cast<const bf16x8*>((char*)SA(b,h)+lds_byte(wr*64+m*16+fr,k*32+fq*8))
;   #define LDB(dst,b,h) for(int n=0;n<2;++n)for(int k=0;k<2;++k) \
;     dst[n][k]=*reinterpret_cast<const bf16x8*>((char*)SB(b,h)+lds_byte(wc*32+n*16+fr,k*32+fq*8))
;   #define MMA(ai,bj,At,Bt_) do{__builtin_amdgcn_s_setprio(1); \
;     for(int m=0;m<4;++m)for(int n=0;n<2;++n)for(int k=0;k<2;++k) \
;       acc[ai][bj][m][n]=__builtin_amdgcn_mfma_f32_16x16x32_bf16(Bt_[n][k],At[m][k],acc[ai][bj][m][n],0,0,0); \
;     __builtin_amdgcn_s_setprio(0);}while(0)
;   #define WAIT_V(n) asm volatile("s_waitcnt vmcnt(" #n ")":::"memory")
;   #define WAIT_L(n) asm volatile("s_waitcnt lgkmcnt(" #n ")":::"memory")
;   #define BAR __builtin_amdgcn_s_barrier()
; template <bool TWO, class MID> ...
;     ...
;   { LDB(B0,1,0); LDA(At,1,0); WAIT_V(2); BAR; WAIT_L(0); MMA(0,0,At,B0); BAR;
;     LDB(B1,1,1); WAIT_V(0); BAR; WAIT_L(0); MMA(0,1,At,B1); BAR;
;     LDA(At,1,1); BAR; WAIT_L(0); MMA(1,0,At,B0); MMA(1,1,At,B1); BAR; }
;   if(wr==0)BAR;
	s_setprio 0
	ds_read_b128 v[130:133], v143
	ds_read_b128 v[148:151], v143 offset:1024
	ds_read_b128 v[208:211], v143 offset:2048
	ds_read_b128 v[220:223], v143 offset:3072
	s_waitcnt vmcnt(0)
	s_setprio 1
	s_barrier
	s_waitcnt lgkmcnt(0)
	v_mfma_f32_16x16x32_bf16 v[98:101], v[130:133], v[26:29], v[212:215]
	v_mfma_f32_16x16x32_bf16 v[26:29], v[208:211], v[26:29], v[168:171]
	v_mfma_f32_16x16x32_bf16 v[114:117], v[220:223], v[30:33], v[26:29]
	v_mfma_f32_16x16x32_bf16 v[26:29], v[130:133], v[42:45], v[86:89]
	v_mfma_f32_16x16x32_bf16 v[102:105], v[148:151], v[46:49], v[26:29]
	v_mfma_f32_16x16x32_bf16 v[26:29], v[208:211], v[42:45], v[82:85]
	v_mfma_f32_16x16x32_bf16 v[118:121], v[148:151], v[30:33], v[98:101]
	v_mfma_f32_16x16x32_bf16 v[98:101], v[220:223], v[46:49], v[26:29]
	v_mfma_f32_16x16x32_bf16 v[26:29], v[130:133], v[184:187], v[172:175]
	v_mfma_f32_16x16x32_bf16 v[86:89], v[148:151], v[188:191], v[26:29]
	v_mfma_f32_16x16x32_bf16 v[26:29], v[208:211], v[184:187], v[176:179]
	v_mfma_f32_16x16x32_bf16 v[82:85], v[220:223], v[188:191], v[26:29]
	v_mfma_f32_16x16x32_bf16 v[26:29], v[130:133], v[196:199], v[70:73]
	v_mfma_f32_16x16x32_bf16 v[70:73], v[148:151], v[204:207], v[26:29]
	v_mfma_f32_16x16x32_bf16 v[26:29], v[208:211], v[196:199], v[66:69]
	v_mfma_f32_16x16x32_bf16 v[66:69], v[220:223], v[204:207], v[26:29]
	s_barrier
	s_setprio 0
	ds_read_b128 v[168:171], v141 offset:49152
	ds_read_b128 v[140:143], v141 offset:50176
	ds_read_b128 v[172:175], v139 offset:49152
	ds_read_b128 v[176:179], v139 offset:50176
	ds_read_b128 v[184:187], v137 offset:49152
	ds_read_b128 v[136:139], v137 offset:50176
	ds_read_b128 v[188:191], v135 offset:49152
	ds_read_b128 v[196:199], v135 offset:50176
	s_setprio 1
	s_barrier
	s_waitcnt lgkmcnt(0)
	v_mfma_f32_16x16x32_bf16 v[26:29], v[10:13], v[168:171], v[62:65]
	v_mfma_f32_16x16x32_bf16 v[62:65], v[14:17], v[140:143], v[26:29]
	v_mfma_f32_16x16x32_bf16 v[26:29], v[180:183], v[168:171], v[58:61]
	v_mfma_f32_16x16x32_bf16 v[58:61], v[144:147], v[140:143], v[26:29]
	v_mfma_f32_16x16x32_bf16 v[26:29], v[10:13], v[172:175], v[54:57]
	v_mfma_f32_16x16x32_bf16 v[46:49], v[14:17], v[176:179], v[26:29]
	v_mfma_f32_16x16x32_bf16 v[26:29], v[180:183], v[172:175], v[50:53]
	v_mfma_f32_16x16x32_bf16 v[42:45], v[144:147], v[176:179], v[26:29]
	v_mfma_f32_16x16x32_bf16 v[26:29], v[10:13], v[184:187], v[200:203]
	v_mfma_f32_16x16x32_bf16 v[10:13], v[10:13], v[188:191], v[38:41]
	v_mfma_f32_16x16x32_bf16 v[30:33], v[14:17], v[136:139], v[26:29]
	v_mfma_f32_16x16x32_bf16 v[26:29], v[180:183], v[184:187], v[216:219]
	v_mfma_f32_16x16x32_bf16 v[14:17], v[14:17], v[196:199], v[10:13]
	v_mfma_f32_16x16x32_bf16 v[10:13], v[180:183], v[188:191], v[34:37]
	v_mfma_f32_16x16x32_bf16 v[26:29], v[144:147], v[136:139], v[26:29]
	v_mfma_f32_16x16x32_bf16 v[10:13], v[144:147], v[196:199], v[10:13]
	s_setprio 0
	s_setprio 1
	v_mfma_f32_16x16x32_bf16 v[34:37], v[130:133], v[168:171], v[152:155]
	v_mfma_f32_16x16x32_bf16 v[54:57], v[148:151], v[140:143], v[34:37]
	v_mfma_f32_16x16x32_bf16 v[34:37], v[208:211], v[168:171], v[156:159]
	v_mfma_f32_16x16x32_bf16 v[18:21], v[208:211], v[172:175], v[18:21]
	v_mfma_f32_16x16x32_bf16 v[50:53], v[220:223], v[140:143], v[34:37]
	v_mfma_f32_16x16x32_bf16 v[22:25], v[130:133], v[172:175], v[22:25]
	v_mfma_f32_16x16x32_bf16 v[34:37], v[220:223], v[176:179], v[18:21]
	v_mfma_f32_16x16x32_bf16 v[18:21], v[130:133], v[184:187], v[160:163]
	v_mfma_f32_16x16x32_bf16 v[38:41], v[148:151], v[176:179], v[22:25]
	v_mfma_f32_16x16x32_bf16 v[22:25], v[148:151], v[136:139], v[18:21]
	v_mfma_f32_16x16x32_bf16 v[18:21], v[208:211], v[184:187], v[164:167]
	v_mfma_f32_16x16x32_bf16 v[6:9], v[130:133], v[188:191], v[6:9]
	v_mfma_f32_16x16x32_bf16 v[2:5], v[208:211], v[188:191], v[2:5]
	v_mfma_f32_16x16x32_bf16 v[18:21], v[220:223], v[136:139], v[18:21]
	v_mfma_f32_16x16x32_bf16 v[6:9], v[148:151], v[196:199], v[6:9]
	v_mfma_f32_16x16x32_bf16 v[2:5], v[220:223], v[196:199], v[2:5]
	s_setprio 0
	v_cmp_gt_u32_e32 vcc, s30, v1
	s_barrier
	s_and_saveexec_b64 s[0:1], vcc
	s_cbranch_execz .LBB0_623
	s_barrier
